# GEMM K-loops: each memory section issues its LDS-DMA loads before its ds_reads (more lead time before the wait two phases later)
# baseline (speedup 1.0000x reference)
.LBB0_123:
	s_add_u32 s24, s22, 0xfff80080
	s_addc_u32 s25, s23, -1
	s_cmp_eq_u32 s53, 28
	s_cselect_b32 s27, s15, s25
	s_cselect_b32 s26, s47, s24
	s_cselect_b32 s25, s13, s52
	s_cselect_b32 s24, s48, s49
	v_lshl_add_u64 v[146:147], s[22:23], 0, v[138:139]
	s_add_i32 m0, s21, 0xc000
	s_nop 0
	global_load_lds_dwordx4 v[146:147], off
	v_lshl_add_u64 v[146:147], s[22:23], 0, v[140:141]
	s_add_i32 m0, s21, 0xe000
	s_nop 0
	global_load_lds_dwordx4 v[146:147], off
	ds_read_b128 v[156:159], v150
	ds_read_b128 v[160:163], v150 offset:1024
	ds_read_b128 v[164:167], v150 offset:2048
	ds_read_b128 v[168:171], v150 offset:3072
	ds_read_b128 v[172:175], v151
	ds_read_b128 v[176:179], v151 offset:1024
	ds_read_b128 v[180:183], v151 offset:2048
	ds_read_b128 v[184:187], v151 offset:3072
	ds_read_b128 v[188:191], v154
	ds_read_b128 v[192:195], v154 offset:1024
	ds_read_b128 v[196:199], v154 offset:2048
	ds_read_b128 v[200:203], v154 offset:3072
	ds_read_b128 v[204:207], v154 offset:4096
	ds_read_b128 v[208:211], v154 offset:5120
	ds_read_b128 v[212:215], v154 offset:6144
	ds_read_b128 v[216:219], v154 offset:7168
	s_waitcnt vmcnt(8)
	s_waitcnt lgkmcnt(0)
	s_barrier
	s_setprio 1
	s_waitcnt lgkmcnt(0)
	v_mfma_f32_16x16x32_bf16 v[126:129], v[156:159], v[188:191], v[126:129]
	v_mfma_f32_16x16x32_bf16 v[122:125], v[164:167], v[188:191], v[122:125]
	v_mfma_f32_16x16x32_bf16 v[118:121], v[156:159], v[196:199], v[118:121]
	v_mfma_f32_16x16x32_bf16 v[110:113], v[164:167], v[196:199], v[110:113]
	v_mfma_f32_16x16x32_bf16 v[102:105], v[156:159], v[204:207], v[102:105]
	v_mfma_f32_16x16x32_bf16 v[94:97], v[164:167], v[204:207], v[94:97]
	v_mfma_f32_16x16x32_bf16 v[86:89], v[156:159], v[212:215], v[86:89]
	v_mfma_f32_16x16x32_bf16 v[78:81], v[164:167], v[212:215], v[78:81]
	v_mfma_f32_16x16x32_bf16 v[126:129], v[160:163], v[192:195], v[126:129]
	v_mfma_f32_16x16x32_bf16 v[122:125], v[168:171], v[192:195], v[122:125]
	v_mfma_f32_16x16x32_bf16 v[118:121], v[160:163], v[200:203], v[118:121]
	v_mfma_f32_16x16x32_bf16 v[110:113], v[168:171], v[200:203], v[110:113]
	v_mfma_f32_16x16x32_bf16 v[102:105], v[160:163], v[208:211], v[102:105]
	v_mfma_f32_16x16x32_bf16 v[94:97], v[168:171], v[208:211], v[94:97]
	v_mfma_f32_16x16x32_bf16 v[86:89], v[160:163], v[216:219], v[86:89]
	v_mfma_f32_16x16x32_bf16 v[78:81], v[168:171], v[216:219], v[78:81]
	s_setprio 0
	s_setprio 1
	v_mfma_f32_16x16x32_bf16 v[114:117], v[172:175], v[188:191], v[114:117]
	v_mfma_f32_16x16x32_bf16 v[106:109], v[180:183], v[188:191], v[106:109]
	v_mfma_f32_16x16x32_bf16 v[98:101], v[172:175], v[196:199], v[98:101]
	v_mfma_f32_16x16x32_bf16 v[90:93], v[180:183], v[196:199], v[90:93]
	v_mfma_f32_16x16x32_bf16 v[82:85], v[172:175], v[204:207], v[82:85]
	v_mfma_f32_16x16x32_bf16 v[74:77], v[180:183], v[204:207], v[74:77]
	v_mfma_f32_16x16x32_bf16 v[70:73], v[172:175], v[212:215], v[70:73]
	v_mfma_f32_16x16x32_bf16 v[66:69], v[180:183], v[212:215], v[66:69]
	v_mfma_f32_16x16x32_bf16 v[114:117], v[176:179], v[192:195], v[114:117]
	v_mfma_f32_16x16x32_bf16 v[106:109], v[184:187], v[192:195], v[106:109]
	v_mfma_f32_16x16x32_bf16 v[98:101], v[176:179], v[200:203], v[98:101]
	v_mfma_f32_16x16x32_bf16 v[90:93], v[184:187], v[200:203], v[90:93]
	v_mfma_f32_16x16x32_bf16 v[82:85], v[176:179], v[208:211], v[82:85]
	v_mfma_f32_16x16x32_bf16 v[74:77], v[184:187], v[208:211], v[74:77]
	v_mfma_f32_16x16x32_bf16 v[70:73], v[176:179], v[216:219], v[70:73]
	v_mfma_f32_16x16x32_bf16 v[66:69], v[184:187], v[216:219], v[66:69]
	s_setprio 0
	s_barrier
	s_add_i32 s54, s44, s34
	v_lshl_add_u64 v[146:147], s[24:25], 0, v[134:135]
	s_mov_b32 m0, s54
	s_nop 0
	global_load_lds_dwordx4 v[146:147], off
	s_add_i32 m0, s54, 0x2000
	s_add_u32 s54, s24, 0x80000
	v_lshl_add_u64 v[220:221], s[24:25], 0, v[130:131]
	s_addc_u32 s55, s25, 0
	s_add_i32 s56, s45, s34
	global_load_lds_dwordx4 v[220:221], off
	v_lshl_add_u64 v[222:223], s[54:55], 0, v[134:135]
	s_mov_b32 m0, s56
	v_lshl_add_u64 v[224:225], s[26:27], 0, v[132:133]
	global_load_lds_dwordx4 v[222:223], off
	v_lshl_add_u64 v[222:223], s[54:55], 0, v[130:131]
	s_add_i32 m0, s56, 0x2000
	s_nop 0
	global_load_lds_dwordx4 v[222:223], off
	v_lshl_add_u64 v[222:223], s[26:27], 0, v[136:137]
	s_mov_b32 m0, s21
	s_nop 0
	global_load_lds_dwordx4 v[222:223], off
	s_mov_b32 m0, s37
	s_nop 0
	global_load_lds_dwordx4 v[224:225], off
	ds_read_b128 v[188:191], v154 offset:16384
	ds_read_b128 v[192:195], v154 offset:17408
	ds_read_b128 v[196:199], v154 offset:18432
	ds_read_b128 v[200:203], v154 offset:19456
	ds_read_b128 v[204:207], v154 offset:20480
	ds_read_b128 v[208:211], v154 offset:21504
	ds_read_b128 v[212:215], v154 offset:22528
	ds_read_b128 v[216:219], v154 offset:23552
	s_waitcnt vmcnt(8)
	s_waitcnt lgkmcnt(0)
	s_barrier
	s_setprio 1
	s_waitcnt lgkmcnt(0)
	v_mfma_f32_16x16x32_bf16 v[62:65], v[156:159], v[188:191], v[62:65]
	v_mfma_f32_16x16x32_bf16 v[58:61], v[164:167], v[188:191], v[58:61]
	v_mfma_f32_16x16x32_bf16 v[54:57], v[156:159], v[196:199], v[54:57]
	v_mfma_f32_16x16x32_bf16 v[46:49], v[164:167], v[196:199], v[46:49]
	v_mfma_f32_16x16x32_bf16 v[38:41], v[156:159], v[204:207], v[38:41]
	v_mfma_f32_16x16x32_bf16 v[30:33], v[164:167], v[204:207], v[30:33]
	v_mfma_f32_16x16x32_bf16 v[22:25], v[156:159], v[212:215], v[22:25]
	v_mfma_f32_16x16x32_bf16 v[14:17], v[164:167], v[212:215], v[14:17]
	v_mfma_f32_16x16x32_bf16 v[62:65], v[160:163], v[192:195], v[62:65]
	v_mfma_f32_16x16x32_bf16 v[58:61], v[168:171], v[192:195], v[58:61]
	v_mfma_f32_16x16x32_bf16 v[54:57], v[160:163], v[200:203], v[54:57]
	v_mfma_f32_16x16x32_bf16 v[46:49], v[168:171], v[200:203], v[46:49]
	v_mfma_f32_16x16x32_bf16 v[38:41], v[160:163], v[208:211], v[38:41]
	v_mfma_f32_16x16x32_bf16 v[30:33], v[168:171], v[208:211], v[30:33]
	v_mfma_f32_16x16x32_bf16 v[22:25], v[160:163], v[216:219], v[22:25]
	v_mfma_f32_16x16x32_bf16 v[14:17], v[168:171], v[216:219], v[14:17]
	s_setprio 0
	s_setprio 1
	v_mfma_f32_16x16x32_bf16 v[50:53], v[172:175], v[188:191], v[50:53]
	v_mfma_f32_16x16x32_bf16 v[42:45], v[180:183], v[188:191], v[42:45]
	v_mfma_f32_16x16x32_bf16 v[34:37], v[172:175], v[196:199], v[34:37]
	v_mfma_f32_16x16x32_bf16 v[26:29], v[180:183], v[196:199], v[26:29]
	v_mfma_f32_16x16x32_bf16 v[18:21], v[172:175], v[204:207], v[18:21]
	v_mfma_f32_16x16x32_bf16 v[10:13], v[180:183], v[204:207], v[10:13]
	v_mfma_f32_16x16x32_bf16 v[6:9], v[172:175], v[212:215], v[6:9]
	v_mfma_f32_16x16x32_bf16 v[2:5], v[180:183], v[212:215], v[2:5]
	v_mfma_f32_16x16x32_bf16 v[50:53], v[176:179], v[192:195], v[50:53]
	v_mfma_f32_16x16x32_bf16 v[42:45], v[184:187], v[192:195], v[42:45]
	v_mfma_f32_16x16x32_bf16 v[34:37], v[176:179], v[200:203], v[34:37]
	v_mfma_f32_16x16x32_bf16 v[26:29], v[184:187], v[200:203], v[26:29]
	v_mfma_f32_16x16x32_bf16 v[18:21], v[176:179], v[208:211], v[18:21]
	v_mfma_f32_16x16x32_bf16 v[10:13], v[184:187], v[208:211], v[10:13]
	v_mfma_f32_16x16x32_bf16 v[6:9], v[176:179], v[216:219], v[6:9]
	v_mfma_f32_16x16x32_bf16 v[2:5], v[184:187], v[216:219], v[2:5]
	s_setprio 0
	s_barrier
	s_add_i32 s54, 0, 0x18000
	v_add_u32_e32 v155, s54, v148
	s_add_i32 s55, 0, 0x1c000
	ds_read_b128 v[156:159], v155
	ds_read_b128 v[160:163], v155 offset:1024
	ds_read_b128 v[164:167], v155 offset:2048
	ds_read_b128 v[168:171], v155 offset:3072
	v_add_u32_e32 v155, s55, v148
	ds_read_b128 v[172:175], v155
	ds_read_b128 v[176:179], v155 offset:1024
	ds_read_b128 v[180:183], v155 offset:2048
	ds_read_b128 v[184:187], v155 offset:3072
	s_add_u32 s26, s26, 0x80000
	s_addc_u32 s27, s27, 0
	s_mov_b32 m0, s38
	v_lshl_add_u64 v[226:227], s[26:27], 0, v[136:137]
	ds_read_b128 v[188:191], v154 offset:32768
	ds_read_b128 v[192:195], v154 offset:33792
	ds_read_b128 v[196:199], v154 offset:34816
	ds_read_b128 v[200:203], v154 offset:35840
	ds_read_b128 v[204:207], v154 offset:36864
	ds_read_b128 v[208:211], v154 offset:37888
	ds_read_b128 v[212:215], v154 offset:38912
	ds_read_b128 v[216:219], v154 offset:39936
	global_load_lds_dwordx4 v[226:227], off
	v_lshl_add_u64 v[226:227], s[26:27], 0, v[132:133]
	s_mov_b32 m0, s39
	s_nop 0
	global_load_lds_dwordx4 v[226:227], off
	s_waitcnt vmcnt(8)
	s_waitcnt lgkmcnt(0)
	s_barrier
	s_setprio 1
	s_waitcnt lgkmcnt(0)
	v_mfma_f32_16x16x32_bf16 v[126:129], v[156:159], v[188:191], v[126:129]
	v_mfma_f32_16x16x32_bf16 v[122:125], v[164:167], v[188:191], v[122:125]
	v_mfma_f32_16x16x32_bf16 v[118:121], v[156:159], v[196:199], v[118:121]
	v_mfma_f32_16x16x32_bf16 v[110:113], v[164:167], v[196:199], v[110:113]
	v_mfma_f32_16x16x32_bf16 v[102:105], v[156:159], v[204:207], v[102:105]
	v_mfma_f32_16x16x32_bf16 v[94:97], v[164:167], v[204:207], v[94:97]
	v_mfma_f32_16x16x32_bf16 v[86:89], v[156:159], v[212:215], v[86:89]
	v_mfma_f32_16x16x32_bf16 v[78:81], v[164:167], v[212:215], v[78:81]
	v_mfma_f32_16x16x32_bf16 v[126:129], v[160:163], v[192:195], v[126:129]
	v_mfma_f32_16x16x32_bf16 v[122:125], v[168:171], v[192:195], v[122:125]
	v_mfma_f32_16x16x32_bf16 v[118:121], v[160:163], v[200:203], v[118:121]
	v_mfma_f32_16x16x32_bf16 v[110:113], v[168:171], v[200:203], v[110:113]
	v_mfma_f32_16x16x32_bf16 v[102:105], v[160:163], v[208:211], v[102:105]
	v_mfma_f32_16x16x32_bf16 v[94:97], v[168:171], v[208:211], v[94:97]
	v_mfma_f32_16x16x32_bf16 v[86:89], v[160:163], v[216:219], v[86:89]
	v_mfma_f32_16x16x32_bf16 v[78:81], v[168:171], v[216:219], v[78:81]
	s_setprio 0
	s_setprio 1
	v_mfma_f32_16x16x32_bf16 v[114:117], v[172:175], v[188:191], v[114:117]
	v_mfma_f32_16x16x32_bf16 v[106:109], v[180:183], v[188:191], v[106:109]
	v_mfma_f32_16x16x32_bf16 v[98:101], v[172:175], v[196:199], v[98:101]
	v_mfma_f32_16x16x32_bf16 v[90:93], v[180:183], v[196:199], v[90:93]
	v_mfma_f32_16x16x32_bf16 v[82:85], v[172:175], v[204:207], v[82:85]
	v_mfma_f32_16x16x32_bf16 v[74:77], v[180:183], v[204:207], v[74:77]
	v_mfma_f32_16x16x32_bf16 v[70:73], v[172:175], v[212:215], v[70:73]
	v_mfma_f32_16x16x32_bf16 v[66:69], v[180:183], v[212:215], v[66:69]
	v_mfma_f32_16x16x32_bf16 v[114:117], v[176:179], v[192:195], v[114:117]
	v_mfma_f32_16x16x32_bf16 v[106:109], v[184:187], v[192:195], v[106:109]
	v_mfma_f32_16x16x32_bf16 v[98:101], v[176:179], v[200:203], v[98:101]
	v_mfma_f32_16x16x32_bf16 v[90:93], v[184:187], v[200:203], v[90:93]
	v_mfma_f32_16x16x32_bf16 v[82:85], v[176:179], v[208:211], v[82:85]
	v_mfma_f32_16x16x32_bf16 v[74:77], v[184:187], v[208:211], v[74:77]
	v_mfma_f32_16x16x32_bf16 v[70:73], v[176:179], v[216:219], v[70:73]
	v_mfma_f32_16x16x32_bf16 v[66:69], v[184:187], v[216:219], v[66:69]
	s_setprio 0
	s_barrier
	s_add_i32 s26, s54, s34
	v_lshl_add_u64 v[146:147], v[146:147], 0, s[8:9]
	s_mov_b32 m0, s26
	s_nop 0
	global_load_lds_dwordx4 v[146:147], off
	s_add_i32 m0, s26, 0x2000
	s_add_u32 s24, s24, 0x80080
	v_lshl_add_u64 v[146:147], v[220:221], 0, s[8:9]
	s_addc_u32 s25, s25, 0
	s_add_i32 s26, s55, s34
	global_load_lds_dwordx4 v[146:147], off
	v_lshl_add_u64 v[146:147], s[24:25], 0, v[134:135]
	s_mov_b32 m0, s26
	s_nop 0
	global_load_lds_dwordx4 v[146:147], off
	v_lshl_add_u64 v[146:147], s[24:25], 0, v[130:131]
	s_add_i32 m0, s26, 0x2000
	s_nop 0
	global_load_lds_dwordx4 v[146:147], off
	v_lshl_add_u64 v[146:147], v[222:223], 0, s[8:9]
	s_mov_b32 m0, s41
	s_nop 0
	global_load_lds_dwordx4 v[146:147], off
	v_lshl_add_u64 v[146:147], v[224:225], 0, s[8:9]
	s_mov_b32 m0, s42
	s_nop 0
	global_load_lds_dwordx4 v[146:147], off
	ds_read_b128 v[188:191], v154 offset:49152
	ds_read_b128 v[192:195], v154 offset:50176
	ds_read_b128 v[196:199], v154 offset:51200
	ds_read_b128 v[200:203], v154 offset:52224
	ds_read_b128 v[204:207], v154 offset:53248
	ds_read_b128 v[208:211], v154 offset:54272
	ds_read_b128 v[212:215], v154 offset:55296
	ds_read_b128 v[216:219], v154 offset:56320
	s_waitcnt vmcnt(8)
	s_waitcnt lgkmcnt(0)
	s_barrier
	s_setprio 1
	s_waitcnt lgkmcnt(0)
	v_mfma_f32_16x16x32_bf16 v[62:65], v[156:159], v[188:191], v[62:65]
	v_mfma_f32_16x16x32_bf16 v[58:61], v[164:167], v[188:191], v[58:61]
	v_mfma_f32_16x16x32_bf16 v[54:57], v[156:159], v[196:199], v[54:57]
	v_mfma_f32_16x16x32_bf16 v[46:49], v[164:167], v[196:199], v[46:49]
	v_mfma_f32_16x16x32_bf16 v[38:41], v[156:159], v[204:207], v[38:41]
	v_mfma_f32_16x16x32_bf16 v[30:33], v[164:167], v[204:207], v[30:33]
	v_mfma_f32_16x16x32_bf16 v[22:25], v[156:159], v[212:215], v[22:25]
	v_mfma_f32_16x16x32_bf16 v[14:17], v[164:167], v[212:215], v[14:17]
	v_mfma_f32_16x16x32_bf16 v[62:65], v[160:163], v[192:195], v[62:65]
	v_mfma_f32_16x16x32_bf16 v[58:61], v[168:171], v[192:195], v[58:61]
	v_mfma_f32_16x16x32_bf16 v[54:57], v[160:163], v[200:203], v[54:57]
	v_mfma_f32_16x16x32_bf16 v[46:49], v[168:171], v[200:203], v[46:49]
	v_mfma_f32_16x16x32_bf16 v[38:41], v[160:163], v[208:211], v[38:41]
	v_mfma_f32_16x16x32_bf16 v[30:33], v[168:171], v[208:211], v[30:33]
	v_mfma_f32_16x16x32_bf16 v[22:25], v[160:163], v[216:219], v[22:25]
	v_mfma_f32_16x16x32_bf16 v[14:17], v[168:171], v[216:219], v[14:17]
	s_setprio 0
	s_setprio 1
	v_mfma_f32_16x16x32_bf16 v[50:53], v[172:175], v[188:191], v[50:53]
	v_mfma_f32_16x16x32_bf16 v[42:45], v[180:183], v[188:191], v[42:45]
	v_mfma_f32_16x16x32_bf16 v[34:37], v[172:175], v[196:199], v[34:37]
	v_mfma_f32_16x16x32_bf16 v[26:29], v[180:183], v[196:199], v[26:29]
	v_mfma_f32_16x16x32_bf16 v[18:21], v[172:175], v[204:207], v[18:21]
	v_mfma_f32_16x16x32_bf16 v[10:13], v[180:183], v[204:207], v[10:13]
	v_mfma_f32_16x16x32_bf16 v[6:9], v[172:175], v[212:215], v[6:9]
	v_mfma_f32_16x16x32_bf16 v[2:5], v[180:183], v[212:215], v[2:5]
	v_mfma_f32_16x16x32_bf16 v[50:53], v[176:179], v[192:195], v[50:53]
	v_mfma_f32_16x16x32_bf16 v[42:45], v[184:187], v[192:195], v[42:45]
	v_mfma_f32_16x16x32_bf16 v[34:37], v[176:179], v[200:203], v[34:37]
	v_mfma_f32_16x16x32_bf16 v[26:29], v[184:187], v[200:203], v[26:29]
	v_mfma_f32_16x16x32_bf16 v[18:21], v[176:179], v[208:211], v[18:21]
	v_mfma_f32_16x16x32_bf16 v[10:13], v[184:187], v[208:211], v[10:13]
	v_mfma_f32_16x16x32_bf16 v[6:9], v[176:179], v[216:219], v[6:9]
	v_mfma_f32_16x16x32_bf16 v[2:5], v[184:187], v[216:219], v[2:5]
	s_setprio 0
	s_barrier
	s_add_i32 s53, s53, 2
	s_add_u32 s22, s22, 0x100
	s_addc_u32 s23, s23, 0
	s_add_u32 s49, s49, 0x100
	s_addc_u32 s52, s52, 0
	s_cmp_gt_u32 s53, 29
	s_cbranch_scc0 .LBB0_123
	s_and_b64 vcc, exec, s[10:11]
	s_cbranch_vccz .LBB0_126
	s_barrier

.LBB0_371:
	s_add_i32 s54, s26, 2
	s_add_u32 s55, s24, 0x80
	s_addc_u32 s27, s25, 0
	s_cmp_eq_u32 s43, s26
	s_cselect_b32 s26, s4, s55
	s_cselect_b32 s27, s5, s27
	s_cselect_b32 s57, s23, s53
	s_cselect_b32 s56, s22, s52
	v_lshl_add_u64 v[218:219], s[24:25], 0, v[138:139]
	s_add_i32 m0, s35, 0xc000
	s_nop 0
	global_load_lds_dwordx4 v[218:219], off
	v_lshl_add_u64 v[218:219], s[24:25], 0, v[140:141]
	s_add_i32 m0, s35, 0xe000
	s_nop 0
	global_load_lds_dwordx4 v[218:219], off
	ds_read_b128 v[154:157], v148
	ds_read_b128 v[158:161], v148 offset:1024
	ds_read_b128 v[162:165], v148 offset:2048
	ds_read_b128 v[166:169], v148 offset:3072
	ds_read_b128 v[170:173], v149
	ds_read_b128 v[174:177], v149 offset:1024
	ds_read_b128 v[178:181], v149 offset:2048
	ds_read_b128 v[182:185], v149 offset:3072
	ds_read_b128 v[186:189], v150
	ds_read_b128 v[190:193], v150 offset:1024
	ds_read_b128 v[194:197], v150 offset:2048
	ds_read_b128 v[198:201], v150 offset:3072
	ds_read_b128 v[202:205], v150 offset:4096
	ds_read_b128 v[206:209], v150 offset:5120
	ds_read_b128 v[210:213], v150 offset:6144
	ds_read_b128 v[214:217], v150 offset:7168
	s_waitcnt vmcnt(8)
	s_waitcnt lgkmcnt(0)
	s_barrier
	s_setprio 1
	s_waitcnt lgkmcnt(0)
	v_mfma_f32_16x16x32_bf16 v[122:125], v[154:157], v[186:189], v[122:125]
	v_mfma_f32_16x16x32_bf16 v[126:129], v[162:165], v[186:189], v[126:129]
	v_mfma_f32_16x16x32_bf16 v[110:113], v[154:157], v[194:197], v[110:113]
	v_mfma_f32_16x16x32_bf16 v[106:109], v[162:165], v[194:197], v[106:109]
	v_mfma_f32_16x16x32_bf16 v[94:97], v[154:157], v[202:205], v[94:97]
	v_mfma_f32_16x16x32_bf16 v[90:93], v[162:165], v[202:205], v[90:93]
	v_mfma_f32_16x16x32_bf16 v[78:81], v[154:157], v[210:213], v[78:81]
	v_mfma_f32_16x16x32_bf16 v[74:77], v[162:165], v[210:213], v[74:77]
	v_mfma_f32_16x16x32_bf16 v[122:125], v[158:161], v[190:193], v[122:125]
	v_mfma_f32_16x16x32_bf16 v[126:129], v[166:169], v[190:193], v[126:129]
	v_mfma_f32_16x16x32_bf16 v[110:113], v[158:161], v[198:201], v[110:113]
	v_mfma_f32_16x16x32_bf16 v[106:109], v[166:169], v[198:201], v[106:109]
	v_mfma_f32_16x16x32_bf16 v[94:97], v[158:161], v[206:209], v[94:97]
	v_mfma_f32_16x16x32_bf16 v[90:93], v[166:169], v[206:209], v[90:93]
	v_mfma_f32_16x16x32_bf16 v[78:81], v[158:161], v[214:217], v[78:81]
	v_mfma_f32_16x16x32_bf16 v[74:77], v[166:169], v[214:217], v[74:77]
	s_setprio 0
	s_setprio 1
	v_mfma_f32_16x16x32_bf16 v[118:121], v[170:173], v[186:189], v[118:121]
	v_mfma_f32_16x16x32_bf16 v[114:117], v[178:181], v[186:189], v[114:117]
	v_mfma_f32_16x16x32_bf16 v[102:105], v[170:173], v[194:197], v[102:105]
	v_mfma_f32_16x16x32_bf16 v[98:101], v[178:181], v[194:197], v[98:101]
	v_mfma_f32_16x16x32_bf16 v[86:89], v[170:173], v[202:205], v[86:89]
	v_mfma_f32_16x16x32_bf16 v[82:85], v[178:181], v[202:205], v[82:85]
	v_mfma_f32_16x16x32_bf16 v[70:73], v[170:173], v[210:213], v[70:73]
	v_mfma_f32_16x16x32_bf16 v[66:69], v[178:181], v[210:213], v[66:69]
	v_mfma_f32_16x16x32_bf16 v[118:121], v[174:177], v[190:193], v[118:121]
	v_mfma_f32_16x16x32_bf16 v[114:117], v[182:185], v[190:193], v[114:117]
	v_mfma_f32_16x16x32_bf16 v[102:105], v[174:177], v[198:201], v[102:105]
	v_mfma_f32_16x16x32_bf16 v[98:101], v[182:185], v[198:201], v[98:101]
	v_mfma_f32_16x16x32_bf16 v[86:89], v[174:177], v[206:209], v[86:89]
	v_mfma_f32_16x16x32_bf16 v[82:85], v[182:185], v[206:209], v[82:85]
	v_mfma_f32_16x16x32_bf16 v[70:73], v[174:177], v[214:217], v[70:73]
	v_mfma_f32_16x16x32_bf16 v[66:69], v[182:185], v[214:217], v[66:69]
	s_setprio 0
	s_barrier
	s_add_i32 s55, s45, s30
	v_lshl_add_u64 v[218:219], s[56:57], 0, v[134:135]
	s_mov_b32 m0, s55
	s_nop 0
	global_load_lds_dwordx4 v[218:219], off
	s_add_i32 m0, s55, 0x2000
	v_lshl_add_u64 v[220:221], s[56:57], 0, v[130:131]
	s_add_u32 s56, s56, s8
	s_addc_u32 s57, s57, s9
	s_add_i32 s55, s46, s30
	global_load_lds_dwordx4 v[220:221], off
	v_lshl_add_u64 v[222:223], s[56:57], 0, v[134:135]
	s_mov_b32 m0, s55
	v_lshl_add_u64 v[224:225], s[56:57], 0, v[130:131]
	global_load_lds_dwordx4 v[222:223], off
	s_add_i32 m0, s55, 0x2000
	v_lshl_add_u64 v[226:227], s[26:27], 0, v[136:137]
	global_load_lds_dwordx4 v[224:225], off
	s_mov_b32 m0, s35
	v_lshl_add_u64 v[228:229], s[26:27], 0, v[132:133]
	global_load_lds_dwordx4 v[226:227], off
	s_mov_b32 m0, s36
	s_nop 0
	global_load_lds_dwordx4 v[228:229], off
	ds_read_b128 v[186:189], v150 offset:16384
	ds_read_b128 v[190:193], v150 offset:17408
	ds_read_b128 v[194:197], v150 offset:18432
	ds_read_b128 v[198:201], v150 offset:19456
	ds_read_b128 v[202:205], v150 offset:20480
	ds_read_b128 v[206:209], v150 offset:21504
	ds_read_b128 v[210:213], v150 offset:22528
	ds_read_b128 v[214:217], v150 offset:23552
	s_waitcnt vmcnt(8)
	s_waitcnt lgkmcnt(0)
	s_barrier
	s_setprio 1
	s_waitcnt lgkmcnt(0)
	v_mfma_f32_16x16x32_bf16 v[62:65], v[154:157], v[186:189], v[62:65]
	v_mfma_f32_16x16x32_bf16 v[58:61], v[162:165], v[186:189], v[58:61]
	v_mfma_f32_16x16x32_bf16 v[46:49], v[154:157], v[194:197], v[46:49]
	v_mfma_f32_16x16x32_bf16 v[42:45], v[162:165], v[194:197], v[42:45]
	v_mfma_f32_16x16x32_bf16 v[30:33], v[154:157], v[202:205], v[30:33]
	v_mfma_f32_16x16x32_bf16 v[26:29], v[162:165], v[202:205], v[26:29]
	v_mfma_f32_16x16x32_bf16 v[14:17], v[154:157], v[210:213], v[14:17]
	v_mfma_f32_16x16x32_bf16 v[10:13], v[162:165], v[210:213], v[10:13]
	v_mfma_f32_16x16x32_bf16 v[62:65], v[158:161], v[190:193], v[62:65]
	v_mfma_f32_16x16x32_bf16 v[58:61], v[166:169], v[190:193], v[58:61]
	v_mfma_f32_16x16x32_bf16 v[46:49], v[158:161], v[198:201], v[46:49]
	v_mfma_f32_16x16x32_bf16 v[42:45], v[166:169], v[198:201], v[42:45]
	v_mfma_f32_16x16x32_bf16 v[30:33], v[158:161], v[206:209], v[30:33]
	v_mfma_f32_16x16x32_bf16 v[26:29], v[166:169], v[206:209], v[26:29]
	v_mfma_f32_16x16x32_bf16 v[14:17], v[158:161], v[214:217], v[14:17]
	v_mfma_f32_16x16x32_bf16 v[10:13], v[166:169], v[214:217], v[10:13]
	s_setprio 0
	s_setprio 1
	v_mfma_f32_16x16x32_bf16 v[54:57], v[170:173], v[186:189], v[54:57]
	v_mfma_f32_16x16x32_bf16 v[50:53], v[178:181], v[186:189], v[50:53]
	v_mfma_f32_16x16x32_bf16 v[38:41], v[170:173], v[194:197], v[38:41]
	v_mfma_f32_16x16x32_bf16 v[34:37], v[178:181], v[194:197], v[34:37]
	v_mfma_f32_16x16x32_bf16 v[22:25], v[170:173], v[202:205], v[22:25]
	v_mfma_f32_16x16x32_bf16 v[18:21], v[178:181], v[202:205], v[18:21]
	v_mfma_f32_16x16x32_bf16 v[6:9], v[170:173], v[210:213], v[6:9]
	v_mfma_f32_16x16x32_bf16 v[2:5], v[178:181], v[210:213], v[2:5]
	v_mfma_f32_16x16x32_bf16 v[54:57], v[174:177], v[190:193], v[54:57]
	v_mfma_f32_16x16x32_bf16 v[50:53], v[182:185], v[190:193], v[50:53]
	v_mfma_f32_16x16x32_bf16 v[38:41], v[174:177], v[198:201], v[38:41]
	v_mfma_f32_16x16x32_bf16 v[34:37], v[182:185], v[198:201], v[34:37]
	v_mfma_f32_16x16x32_bf16 v[22:25], v[174:177], v[206:209], v[22:25]
	v_mfma_f32_16x16x32_bf16 v[18:21], v[182:185], v[206:209], v[18:21]
	v_mfma_f32_16x16x32_bf16 v[6:9], v[174:177], v[214:217], v[6:9]
	v_mfma_f32_16x16x32_bf16 v[2:5], v[182:185], v[214:217], v[2:5]
	s_setprio 0
	s_barrier
	s_add_i32 s55, 0, 0x18000
	v_add_u32_e32 v151, s55, v146
	s_add_i32 s56, 0, 0x1c000
	ds_read_b128 v[154:157], v151
	ds_read_b128 v[158:161], v151 offset:1024
	ds_read_b128 v[162:165], v151 offset:2048
	ds_read_b128 v[166:169], v151 offset:3072
	v_add_u32_e32 v151, s56, v146
	ds_read_b128 v[170:173], v151
	ds_read_b128 v[174:177], v151 offset:1024
	ds_read_b128 v[178:181], v151 offset:2048
	ds_read_b128 v[182:185], v151 offset:3072
	s_add_u32 s26, s26, s8
	s_addc_u32 s27, s27, s9
	s_mov_b32 m0, s37
	v_lshl_add_u64 v[230:231], s[26:27], 0, v[136:137]
	ds_read_b128 v[186:189], v150 offset:32768
	ds_read_b128 v[190:193], v150 offset:33792
	ds_read_b128 v[194:197], v150 offset:34816
	ds_read_b128 v[198:201], v150 offset:35840
	ds_read_b128 v[202:205], v150 offset:36864
	ds_read_b128 v[206:209], v150 offset:37888
	ds_read_b128 v[210:213], v150 offset:38912
	ds_read_b128 v[214:217], v150 offset:39936
	global_load_lds_dwordx4 v[230:231], off
	v_lshl_add_u64 v[230:231], s[26:27], 0, v[132:133]
	s_mov_b32 m0, s38
	s_nop 0
	global_load_lds_dwordx4 v[230:231], off
	s_waitcnt vmcnt(8)
	s_waitcnt lgkmcnt(0)
	s_barrier
	s_setprio 1
	s_waitcnt lgkmcnt(0)
	v_mfma_f32_16x16x32_bf16 v[122:125], v[154:157], v[186:189], v[122:125]
	v_mfma_f32_16x16x32_bf16 v[126:129], v[162:165], v[186:189], v[126:129]
	v_mfma_f32_16x16x32_bf16 v[110:113], v[154:157], v[194:197], v[110:113]
	v_mfma_f32_16x16x32_bf16 v[106:109], v[162:165], v[194:197], v[106:109]
	v_mfma_f32_16x16x32_bf16 v[94:97], v[154:157], v[202:205], v[94:97]
	v_mfma_f32_16x16x32_bf16 v[90:93], v[162:165], v[202:205], v[90:93]
	v_mfma_f32_16x16x32_bf16 v[78:81], v[154:157], v[210:213], v[78:81]
	v_mfma_f32_16x16x32_bf16 v[74:77], v[162:165], v[210:213], v[74:77]
	v_mfma_f32_16x16x32_bf16 v[122:125], v[158:161], v[190:193], v[122:125]
	v_mfma_f32_16x16x32_bf16 v[126:129], v[166:169], v[190:193], v[126:129]
	v_mfma_f32_16x16x32_bf16 v[110:113], v[158:161], v[198:201], v[110:113]
	v_mfma_f32_16x16x32_bf16 v[106:109], v[166:169], v[198:201], v[106:109]
	v_mfma_f32_16x16x32_bf16 v[94:97], v[158:161], v[206:209], v[94:97]
	v_mfma_f32_16x16x32_bf16 v[90:93], v[166:169], v[206:209], v[90:93]
	v_mfma_f32_16x16x32_bf16 v[78:81], v[158:161], v[214:217], v[78:81]
	v_mfma_f32_16x16x32_bf16 v[74:77], v[166:169], v[214:217], v[74:77]
	s_setprio 0
	s_setprio 1
	v_mfma_f32_16x16x32_bf16 v[118:121], v[170:173], v[186:189], v[118:121]
	v_mfma_f32_16x16x32_bf16 v[114:117], v[178:181], v[186:189], v[114:117]
	v_mfma_f32_16x16x32_bf16 v[102:105], v[170:173], v[194:197], v[102:105]
	v_mfma_f32_16x16x32_bf16 v[98:101], v[178:181], v[194:197], v[98:101]
	v_mfma_f32_16x16x32_bf16 v[86:89], v[170:173], v[202:205], v[86:89]
	v_mfma_f32_16x16x32_bf16 v[82:85], v[178:181], v[202:205], v[82:85]
	v_mfma_f32_16x16x32_bf16 v[70:73], v[170:173], v[210:213], v[70:73]
	v_mfma_f32_16x16x32_bf16 v[66:69], v[178:181], v[210:213], v[66:69]
	v_mfma_f32_16x16x32_bf16 v[118:121], v[174:177], v[190:193], v[118:121]
	v_mfma_f32_16x16x32_bf16 v[114:117], v[182:185], v[190:193], v[114:117]
	v_mfma_f32_16x16x32_bf16 v[102:105], v[174:177], v[198:201], v[102:105]
	v_mfma_f32_16x16x32_bf16 v[98:101], v[182:185], v[198:201], v[98:101]
	v_mfma_f32_16x16x32_bf16 v[86:89], v[174:177], v[206:209], v[86:89]
	v_mfma_f32_16x16x32_bf16 v[82:85], v[182:185], v[206:209], v[82:85]
	v_mfma_f32_16x16x32_bf16 v[70:73], v[174:177], v[214:217], v[70:73]
	v_mfma_f32_16x16x32_bf16 v[66:69], v[182:185], v[214:217], v[66:69]
	s_setprio 0
	s_barrier
	s_add_i32 s26, s55, s30
	v_lshl_add_u64 v[218:219], v[218:219], 0, s[16:17]
	s_mov_b32 m0, s26
	s_nop 0
	global_load_lds_dwordx4 v[218:219], off
	v_lshl_add_u64 v[218:219], v[220:221], 0, s[16:17]
	s_add_i32 m0, s26, 0x2000
	s_add_i32 s26, s56, s30
	global_load_lds_dwordx4 v[218:219], off
	v_lshl_add_u64 v[218:219], v[222:223], 0, s[16:17]
	s_mov_b32 m0, s26
	s_nop 0
	global_load_lds_dwordx4 v[218:219], off
	v_lshl_add_u64 v[218:219], v[224:225], 0, s[16:17]
	s_add_i32 m0, s26, 0x2000
	s_nop 0
	global_load_lds_dwordx4 v[218:219], off
	v_lshl_add_u64 v[218:219], v[226:227], 0, s[16:17]
	s_mov_b32 m0, s39
	s_nop 0
	global_load_lds_dwordx4 v[218:219], off
	v_lshl_add_u64 v[218:219], v[228:229], 0, s[16:17]
	s_mov_b32 m0, s40
	s_nop 0
	global_load_lds_dwordx4 v[218:219], off
	ds_read_b128 v[186:189], v150 offset:49152
	ds_read_b128 v[190:193], v150 offset:50176
	ds_read_b128 v[194:197], v150 offset:51200
	ds_read_b128 v[198:201], v150 offset:52224
	ds_read_b128 v[202:205], v150 offset:53248
	ds_read_b128 v[206:209], v150 offset:54272
	ds_read_b128 v[210:213], v150 offset:55296
	ds_read_b128 v[214:217], v150 offset:56320
	s_waitcnt vmcnt(8)
	s_waitcnt lgkmcnt(0)
	s_barrier
	s_setprio 1
	s_waitcnt lgkmcnt(0)
	v_mfma_f32_16x16x32_bf16 v[62:65], v[154:157], v[186:189], v[62:65]
	v_mfma_f32_16x16x32_bf16 v[58:61], v[162:165], v[186:189], v[58:61]
	v_mfma_f32_16x16x32_bf16 v[46:49], v[154:157], v[194:197], v[46:49]
	v_mfma_f32_16x16x32_bf16 v[42:45], v[162:165], v[194:197], v[42:45]
	v_mfma_f32_16x16x32_bf16 v[30:33], v[154:157], v[202:205], v[30:33]
	v_mfma_f32_16x16x32_bf16 v[26:29], v[162:165], v[202:205], v[26:29]
	v_mfma_f32_16x16x32_bf16 v[14:17], v[154:157], v[210:213], v[14:17]
	v_mfma_f32_16x16x32_bf16 v[10:13], v[162:165], v[210:213], v[10:13]
	v_mfma_f32_16x16x32_bf16 v[62:65], v[158:161], v[190:193], v[62:65]
	v_mfma_f32_16x16x32_bf16 v[58:61], v[166:169], v[190:193], v[58:61]
	v_mfma_f32_16x16x32_bf16 v[46:49], v[158:161], v[198:201], v[46:49]
	v_mfma_f32_16x16x32_bf16 v[42:45], v[166:169], v[198:201], v[42:45]
	v_mfma_f32_16x16x32_bf16 v[30:33], v[158:161], v[206:209], v[30:33]
	v_mfma_f32_16x16x32_bf16 v[26:29], v[166:169], v[206:209], v[26:29]
	v_mfma_f32_16x16x32_bf16 v[14:17], v[158:161], v[214:217], v[14:17]
	v_mfma_f32_16x16x32_bf16 v[10:13], v[166:169], v[214:217], v[10:13]
	s_setprio 0
	s_setprio 1
	v_mfma_f32_16x16x32_bf16 v[54:57], v[170:173], v[186:189], v[54:57]
	v_mfma_f32_16x16x32_bf16 v[50:53], v[178:181], v[186:189], v[50:53]
	v_mfma_f32_16x16x32_bf16 v[38:41], v[170:173], v[194:197], v[38:41]
	v_mfma_f32_16x16x32_bf16 v[34:37], v[178:181], v[194:197], v[34:37]
	v_mfma_f32_16x16x32_bf16 v[22:25], v[170:173], v[202:205], v[22:25]
	v_mfma_f32_16x16x32_bf16 v[18:21], v[178:181], v[202:205], v[18:21]
	v_mfma_f32_16x16x32_bf16 v[6:9], v[170:173], v[210:213], v[6:9]
	v_mfma_f32_16x16x32_bf16 v[2:5], v[178:181], v[210:213], v[2:5]
	v_mfma_f32_16x16x32_bf16 v[54:57], v[174:177], v[190:193], v[54:57]
	v_mfma_f32_16x16x32_bf16 v[50:53], v[182:185], v[190:193], v[50:53]
	v_mfma_f32_16x16x32_bf16 v[38:41], v[174:177], v[198:201], v[38:41]
	v_mfma_f32_16x16x32_bf16 v[34:37], v[182:185], v[198:201], v[34:37]
	v_mfma_f32_16x16x32_bf16 v[22:25], v[174:177], v[206:209], v[22:25]
	v_mfma_f32_16x16x32_bf16 v[18:21], v[182:185], v[206:209], v[18:21]
	v_mfma_f32_16x16x32_bf16 v[6:9], v[174:177], v[214:217], v[6:9]
	v_mfma_f32_16x16x32_bf16 v[2:5], v[182:185], v[214:217], v[2:5]
	s_setprio 0
	s_barrier
	s_add_u32 s24, s24, 0x100
	s_addc_u32 s25, s25, 0
	s_add_u32 s52, s52, 0x100
	s_addc_u32 s53, s53, 0
	s_cmp_ge_i32 s54, s41
	s_mov_b32 s26, s54
	s_cbranch_scc0 .LBB0_371

.LBB0_568:
	s_add_u32 s30, s28, 0xfff80080
	s_addc_u32 s31, s29, -1
	s_cmp_eq_u32 s58, 28
	s_cselect_b32 s35, s19, s31
	s_cselect_b32 s34, s54, s30
	s_cselect_b32 s31, s21, s57
	s_cselect_b32 s30, s55, s56
	v_lshl_add_u64 v[150:151], s[28:29], 0, v[142:143]
	s_add_i32 m0, s27, 0xc000
	s_nop 0
	global_load_lds_dwordx4 v[150:151], off
	v_lshl_add_u64 v[150:151], s[28:29], 0, v[144:145]
	s_add_i32 m0, s27, 0xe000
	s_nop 0
	global_load_lds_dwordx4 v[150:151], off
	ds_read_b128 v[166:169], v162
	ds_read_b128 v[170:173], v162 offset:1024
	ds_read_b128 v[174:177], v162 offset:2048
	ds_read_b128 v[178:181], v162 offset:3072
	ds_read_b128 v[182:185], v163
	ds_read_b128 v[186:189], v163 offset:1024
	ds_read_b128 v[190:193], v163 offset:2048
	ds_read_b128 v[194:197], v163 offset:3072
	ds_read_b128 v[198:201], v164
	ds_read_b128 v[202:205], v164 offset:1024
	ds_read_b128 v[206:209], v164 offset:2048
	ds_read_b128 v[210:213], v164 offset:3072
	ds_read_b128 v[214:217], v164 offset:4096
	ds_read_b128 v[218:221], v164 offset:5120
	ds_read_b128 v[222:225], v164 offset:6144
	ds_read_b128 v[226:229], v164 offset:7168
	s_waitcnt vmcnt(8)
	s_waitcnt lgkmcnt(0)
	s_barrier
	s_setprio 1
	s_waitcnt lgkmcnt(0)
	v_mfma_f32_16x16x32_bf16 v[126:129], v[166:169], v[198:201], v[126:129]
	v_mfma_f32_16x16x32_bf16 v[122:125], v[174:177], v[198:201], v[122:125]
	v_mfma_f32_16x16x32_bf16 v[118:121], v[166:169], v[206:209], v[118:121]
	v_mfma_f32_16x16x32_bf16 v[110:113], v[174:177], v[206:209], v[110:113]
	v_mfma_f32_16x16x32_bf16 v[102:105], v[166:169], v[214:217], v[102:105]
	v_mfma_f32_16x16x32_bf16 v[94:97], v[174:177], v[214:217], v[94:97]
	v_mfma_f32_16x16x32_bf16 v[86:89], v[166:169], v[222:225], v[86:89]
	v_mfma_f32_16x16x32_bf16 v[78:81], v[174:177], v[222:225], v[78:81]
	v_mfma_f32_16x16x32_bf16 v[126:129], v[170:173], v[202:205], v[126:129]
	v_mfma_f32_16x16x32_bf16 v[122:125], v[178:181], v[202:205], v[122:125]
	v_mfma_f32_16x16x32_bf16 v[118:121], v[170:173], v[210:213], v[118:121]
	v_mfma_f32_16x16x32_bf16 v[110:113], v[178:181], v[210:213], v[110:113]
	v_mfma_f32_16x16x32_bf16 v[102:105], v[170:173], v[218:221], v[102:105]
	v_mfma_f32_16x16x32_bf16 v[94:97], v[178:181], v[218:221], v[94:97]
	v_mfma_f32_16x16x32_bf16 v[86:89], v[170:173], v[226:229], v[86:89]
	v_mfma_f32_16x16x32_bf16 v[78:81], v[178:181], v[226:229], v[78:81]
	s_setprio 0
	s_setprio 1
	v_mfma_f32_16x16x32_bf16 v[114:117], v[182:185], v[198:201], v[114:117]
	v_mfma_f32_16x16x32_bf16 v[106:109], v[190:193], v[198:201], v[106:109]
	v_mfma_f32_16x16x32_bf16 v[98:101], v[182:185], v[206:209], v[98:101]
	v_mfma_f32_16x16x32_bf16 v[90:93], v[190:193], v[206:209], v[90:93]
	v_mfma_f32_16x16x32_bf16 v[82:85], v[182:185], v[214:217], v[82:85]
	v_mfma_f32_16x16x32_bf16 v[74:77], v[190:193], v[214:217], v[74:77]
	v_mfma_f32_16x16x32_bf16 v[70:73], v[182:185], v[222:225], v[70:73]
	v_mfma_f32_16x16x32_bf16 v[66:69], v[190:193], v[222:225], v[66:69]
	v_mfma_f32_16x16x32_bf16 v[114:117], v[186:189], v[202:205], v[114:117]
	v_mfma_f32_16x16x32_bf16 v[106:109], v[194:197], v[202:205], v[106:109]
	v_mfma_f32_16x16x32_bf16 v[98:101], v[186:189], v[210:213], v[98:101]
	v_mfma_f32_16x16x32_bf16 v[90:93], v[194:197], v[210:213], v[90:93]
	v_mfma_f32_16x16x32_bf16 v[82:85], v[186:189], v[218:221], v[82:85]
	v_mfma_f32_16x16x32_bf16 v[74:77], v[194:197], v[218:221], v[74:77]
	v_mfma_f32_16x16x32_bf16 v[70:73], v[186:189], v[226:229], v[70:73]
	v_mfma_f32_16x16x32_bf16 v[66:69], v[194:197], v[226:229], v[66:69]
	s_setprio 0
	s_barrier
	s_add_i32 s59, s47, s37
	v_lshl_add_u64 v[150:151], s[30:31], 0, v[134:135]
	s_mov_b32 m0, s59
	s_nop 0
	global_load_lds_dwordx4 v[150:151], off
	s_add_i32 m0, s59, 0x2000
	s_add_u32 s60, s30, 0x80000
	v_lshl_add_u64 v[230:231], s[30:31], 0, v[138:139]
	s_addc_u32 s61, s31, 0
	s_add_i32 s59, s48, s37
	global_load_lds_dwordx4 v[230:231], off
	v_lshl_add_u64 v[232:233], s[60:61], 0, v[134:135]
	s_mov_b32 m0, s59
	v_lshl_add_u64 v[234:235], s[34:35], 0, v[136:137]
	global_load_lds_dwordx4 v[232:233], off
	v_lshl_add_u64 v[232:233], s[60:61], 0, v[138:139]
	s_add_i32 m0, s59, 0x2000
	s_nop 0
	global_load_lds_dwordx4 v[232:233], off
	v_lshl_add_u64 v[232:233], s[34:35], 0, v[132:133]
	s_mov_b32 m0, s27
	s_nop 0
	global_load_lds_dwordx4 v[232:233], off
	s_mov_b32 m0, s40
	s_nop 0
	global_load_lds_dwordx4 v[234:235], off
	ds_read_b128 v[198:201], v164 offset:16384
	ds_read_b128 v[202:205], v164 offset:17408
	ds_read_b128 v[206:209], v164 offset:18432
	ds_read_b128 v[210:213], v164 offset:19456
	ds_read_b128 v[214:217], v164 offset:20480
	ds_read_b128 v[218:221], v164 offset:21504
	ds_read_b128 v[222:225], v164 offset:22528
	ds_read_b128 v[226:229], v164 offset:23552
	s_waitcnt vmcnt(8)
	s_waitcnt lgkmcnt(0)
	s_barrier
	s_setprio 1
	s_waitcnt lgkmcnt(0)
	v_mfma_f32_16x16x32_bf16 v[62:65], v[166:169], v[198:201], v[62:65]
	v_mfma_f32_16x16x32_bf16 v[58:61], v[174:177], v[198:201], v[58:61]
	v_mfma_f32_16x16x32_bf16 v[54:57], v[166:169], v[206:209], v[54:57]
	v_mfma_f32_16x16x32_bf16 v[46:49], v[174:177], v[206:209], v[46:49]
	v_mfma_f32_16x16x32_bf16 v[38:41], v[166:169], v[214:217], v[38:41]
	v_mfma_f32_16x16x32_bf16 v[30:33], v[174:177], v[214:217], v[30:33]
	v_mfma_f32_16x16x32_bf16 v[22:25], v[166:169], v[222:225], v[22:25]
	v_mfma_f32_16x16x32_bf16 v[14:17], v[174:177], v[222:225], v[14:17]
	v_mfma_f32_16x16x32_bf16 v[62:65], v[170:173], v[202:205], v[62:65]
	v_mfma_f32_16x16x32_bf16 v[58:61], v[178:181], v[202:205], v[58:61]
	v_mfma_f32_16x16x32_bf16 v[54:57], v[170:173], v[210:213], v[54:57]
	v_mfma_f32_16x16x32_bf16 v[46:49], v[178:181], v[210:213], v[46:49]
	v_mfma_f32_16x16x32_bf16 v[38:41], v[170:173], v[218:221], v[38:41]
	v_mfma_f32_16x16x32_bf16 v[30:33], v[178:181], v[218:221], v[30:33]
	v_mfma_f32_16x16x32_bf16 v[22:25], v[170:173], v[226:229], v[22:25]
	v_mfma_f32_16x16x32_bf16 v[14:17], v[178:181], v[226:229], v[14:17]
	s_setprio 0
	s_setprio 1
	v_mfma_f32_16x16x32_bf16 v[50:53], v[182:185], v[198:201], v[50:53]
	v_mfma_f32_16x16x32_bf16 v[42:45], v[190:193], v[198:201], v[42:45]
	v_mfma_f32_16x16x32_bf16 v[34:37], v[182:185], v[206:209], v[34:37]
	v_mfma_f32_16x16x32_bf16 v[26:29], v[190:193], v[206:209], v[26:29]
	v_mfma_f32_16x16x32_bf16 v[18:21], v[182:185], v[214:217], v[18:21]
	v_mfma_f32_16x16x32_bf16 v[10:13], v[190:193], v[214:217], v[10:13]
	v_mfma_f32_16x16x32_bf16 v[6:9], v[182:185], v[222:225], v[6:9]
	v_mfma_f32_16x16x32_bf16 v[2:5], v[190:193], v[222:225], v[2:5]
	v_mfma_f32_16x16x32_bf16 v[50:53], v[186:189], v[202:205], v[50:53]
	v_mfma_f32_16x16x32_bf16 v[42:45], v[194:197], v[202:205], v[42:45]
	v_mfma_f32_16x16x32_bf16 v[34:37], v[186:189], v[210:213], v[34:37]
	v_mfma_f32_16x16x32_bf16 v[26:29], v[194:197], v[210:213], v[26:29]
	v_mfma_f32_16x16x32_bf16 v[18:21], v[186:189], v[218:221], v[18:21]
	v_mfma_f32_16x16x32_bf16 v[10:13], v[194:197], v[218:221], v[10:13]
	v_mfma_f32_16x16x32_bf16 v[6:9], v[186:189], v[226:229], v[6:9]
	v_mfma_f32_16x16x32_bf16 v[2:5], v[194:197], v[226:229], v[2:5]
	s_setprio 0
	s_barrier
	s_add_i32 s59, 0, 0x18000
	v_add_u32_e32 v165, s59, v160
	s_add_i32 s60, 0, 0x1c000
	ds_read_b128 v[166:169], v165
	ds_read_b128 v[170:173], v165 offset:1024
	ds_read_b128 v[174:177], v165 offset:2048
	ds_read_b128 v[178:181], v165 offset:3072
	v_add_u32_e32 v165, s60, v160
	ds_read_b128 v[182:185], v165
	ds_read_b128 v[186:189], v165 offset:1024
	ds_read_b128 v[190:193], v165 offset:2048
	ds_read_b128 v[194:197], v165 offset:3072
	s_add_u32 s34, s34, 0x80000
	s_addc_u32 s35, s35, 0
	s_mov_b32 m0, s41
	v_lshl_add_u64 v[236:237], s[34:35], 0, v[132:133]
	ds_read_b128 v[198:201], v164 offset:32768
	ds_read_b128 v[202:205], v164 offset:33792
	ds_read_b128 v[206:209], v164 offset:34816
	ds_read_b128 v[210:213], v164 offset:35840
	ds_read_b128 v[214:217], v164 offset:36864
	ds_read_b128 v[218:221], v164 offset:37888
	ds_read_b128 v[222:225], v164 offset:38912
	ds_read_b128 v[226:229], v164 offset:39936
	global_load_lds_dwordx4 v[236:237], off
	v_lshl_add_u64 v[236:237], s[34:35], 0, v[136:137]
	s_mov_b32 m0, s44
	s_nop 0
	global_load_lds_dwordx4 v[236:237], off
	s_waitcnt vmcnt(8)
	s_waitcnt lgkmcnt(0)
	s_barrier
	s_setprio 1
	s_waitcnt lgkmcnt(0)
	v_mfma_f32_16x16x32_bf16 v[126:129], v[166:169], v[198:201], v[126:129]
	v_mfma_f32_16x16x32_bf16 v[122:125], v[174:177], v[198:201], v[122:125]
	v_mfma_f32_16x16x32_bf16 v[118:121], v[166:169], v[206:209], v[118:121]
	v_mfma_f32_16x16x32_bf16 v[110:113], v[174:177], v[206:209], v[110:113]
	v_mfma_f32_16x16x32_bf16 v[102:105], v[166:169], v[214:217], v[102:105]
	v_mfma_f32_16x16x32_bf16 v[94:97], v[174:177], v[214:217], v[94:97]
	v_mfma_f32_16x16x32_bf16 v[86:89], v[166:169], v[222:225], v[86:89]
	v_mfma_f32_16x16x32_bf16 v[78:81], v[174:177], v[222:225], v[78:81]
	v_mfma_f32_16x16x32_bf16 v[126:129], v[170:173], v[202:205], v[126:129]
	v_mfma_f32_16x16x32_bf16 v[122:125], v[178:181], v[202:205], v[122:125]
	v_mfma_f32_16x16x32_bf16 v[118:121], v[170:173], v[210:213], v[118:121]
	v_mfma_f32_16x16x32_bf16 v[110:113], v[178:181], v[210:213], v[110:113]
	v_mfma_f32_16x16x32_bf16 v[102:105], v[170:173], v[218:221], v[102:105]
	v_mfma_f32_16x16x32_bf16 v[94:97], v[178:181], v[218:221], v[94:97]
	v_mfma_f32_16x16x32_bf16 v[86:89], v[170:173], v[226:229], v[86:89]
	v_mfma_f32_16x16x32_bf16 v[78:81], v[178:181], v[226:229], v[78:81]
	s_setprio 0
	s_setprio 1
	v_mfma_f32_16x16x32_bf16 v[114:117], v[182:185], v[198:201], v[114:117]
	v_mfma_f32_16x16x32_bf16 v[106:109], v[190:193], v[198:201], v[106:109]
	v_mfma_f32_16x16x32_bf16 v[98:101], v[182:185], v[206:209], v[98:101]
	v_mfma_f32_16x16x32_bf16 v[90:93], v[190:193], v[206:209], v[90:93]
	v_mfma_f32_16x16x32_bf16 v[82:85], v[182:185], v[214:217], v[82:85]
	v_mfma_f32_16x16x32_bf16 v[74:77], v[190:193], v[214:217], v[74:77]
	v_mfma_f32_16x16x32_bf16 v[70:73], v[182:185], v[222:225], v[70:73]
	v_mfma_f32_16x16x32_bf16 v[66:69], v[190:193], v[222:225], v[66:69]
	v_mfma_f32_16x16x32_bf16 v[114:117], v[186:189], v[202:205], v[114:117]
	v_mfma_f32_16x16x32_bf16 v[106:109], v[194:197], v[202:205], v[106:109]
	v_mfma_f32_16x16x32_bf16 v[98:101], v[186:189], v[210:213], v[98:101]
	v_mfma_f32_16x16x32_bf16 v[90:93], v[194:197], v[210:213], v[90:93]
	v_mfma_f32_16x16x32_bf16 v[82:85], v[186:189], v[218:221], v[82:85]
	v_mfma_f32_16x16x32_bf16 v[74:77], v[194:197], v[218:221], v[74:77]
	v_mfma_f32_16x16x32_bf16 v[70:73], v[186:189], v[226:229], v[70:73]
	v_mfma_f32_16x16x32_bf16 v[66:69], v[194:197], v[226:229], v[66:69]
	s_setprio 0
	s_barrier
	s_add_i32 s34, s59, s37
	v_lshl_add_u64 v[150:151], v[150:151], 0, s[12:13]
	s_mov_b32 m0, s34
	s_nop 0
	global_load_lds_dwordx4 v[150:151], off
	s_add_i32 m0, s34, 0x2000
	s_add_u32 s30, s30, 0x80080
	v_lshl_add_u64 v[150:151], v[230:231], 0, s[12:13]
	s_addc_u32 s31, s31, 0
	s_add_i32 s34, s60, s37
	global_load_lds_dwordx4 v[150:151], off
	v_lshl_add_u64 v[150:151], s[30:31], 0, v[134:135]
	s_mov_b32 m0, s34
	s_nop 0
	global_load_lds_dwordx4 v[150:151], off
	v_lshl_add_u64 v[150:151], s[30:31], 0, v[138:139]
	s_add_i32 m0, s34, 0x2000
	s_nop 0
	global_load_lds_dwordx4 v[150:151], off
	v_lshl_add_u64 v[150:151], v[232:233], 0, s[12:13]
	s_mov_b32 m0, s45
	s_nop 0
	global_load_lds_dwordx4 v[150:151], off
	v_lshl_add_u64 v[150:151], v[234:235], 0, s[12:13]
	s_mov_b32 m0, s46
	s_nop 0
	global_load_lds_dwordx4 v[150:151], off
	ds_read_b128 v[198:201], v164 offset:49152
	ds_read_b128 v[202:205], v164 offset:50176
	ds_read_b128 v[206:209], v164 offset:51200
	ds_read_b128 v[210:213], v164 offset:52224
	ds_read_b128 v[214:217], v164 offset:53248
	ds_read_b128 v[218:221], v164 offset:54272
	ds_read_b128 v[222:225], v164 offset:55296
	ds_read_b128 v[226:229], v164 offset:56320
	s_waitcnt vmcnt(8)
	s_waitcnt lgkmcnt(0)
	s_barrier
	s_setprio 1
	s_waitcnt lgkmcnt(0)
	v_mfma_f32_16x16x32_bf16 v[62:65], v[166:169], v[198:201], v[62:65]
	v_mfma_f32_16x16x32_bf16 v[58:61], v[174:177], v[198:201], v[58:61]
	v_mfma_f32_16x16x32_bf16 v[54:57], v[166:169], v[206:209], v[54:57]
	v_mfma_f32_16x16x32_bf16 v[46:49], v[174:177], v[206:209], v[46:49]
	v_mfma_f32_16x16x32_bf16 v[38:41], v[166:169], v[214:217], v[38:41]
	v_mfma_f32_16x16x32_bf16 v[30:33], v[174:177], v[214:217], v[30:33]
	v_mfma_f32_16x16x32_bf16 v[22:25], v[166:169], v[222:225], v[22:25]
	v_mfma_f32_16x16x32_bf16 v[14:17], v[174:177], v[222:225], v[14:17]
	v_mfma_f32_16x16x32_bf16 v[62:65], v[170:173], v[202:205], v[62:65]
	v_mfma_f32_16x16x32_bf16 v[58:61], v[178:181], v[202:205], v[58:61]
	v_mfma_f32_16x16x32_bf16 v[54:57], v[170:173], v[210:213], v[54:57]
	v_mfma_f32_16x16x32_bf16 v[46:49], v[178:181], v[210:213], v[46:49]
	v_mfma_f32_16x16x32_bf16 v[38:41], v[170:173], v[218:221], v[38:41]
	v_mfma_f32_16x16x32_bf16 v[30:33], v[178:181], v[218:221], v[30:33]
	v_mfma_f32_16x16x32_bf16 v[22:25], v[170:173], v[226:229], v[22:25]
	v_mfma_f32_16x16x32_bf16 v[14:17], v[178:181], v[226:229], v[14:17]
	s_setprio 0
	s_setprio 1
	v_mfma_f32_16x16x32_bf16 v[50:53], v[182:185], v[198:201], v[50:53]
	v_mfma_f32_16x16x32_bf16 v[42:45], v[190:193], v[198:201], v[42:45]
	v_mfma_f32_16x16x32_bf16 v[34:37], v[182:185], v[206:209], v[34:37]
	v_mfma_f32_16x16x32_bf16 v[26:29], v[190:193], v[206:209], v[26:29]
	v_mfma_f32_16x16x32_bf16 v[18:21], v[182:185], v[214:217], v[18:21]
	v_mfma_f32_16x16x32_bf16 v[10:13], v[190:193], v[214:217], v[10:13]
	v_mfma_f32_16x16x32_bf16 v[6:9], v[182:185], v[222:225], v[6:9]
	v_mfma_f32_16x16x32_bf16 v[2:5], v[190:193], v[222:225], v[2:5]
	v_mfma_f32_16x16x32_bf16 v[50:53], v[186:189], v[202:205], v[50:53]
	v_mfma_f32_16x16x32_bf16 v[42:45], v[194:197], v[202:205], v[42:45]
	v_mfma_f32_16x16x32_bf16 v[34:37], v[186:189], v[210:213], v[34:37]
	v_mfma_f32_16x16x32_bf16 v[26:29], v[194:197], v[210:213], v[26:29]
	v_mfma_f32_16x16x32_bf16 v[18:21], v[186:189], v[218:221], v[18:21]
	v_mfma_f32_16x16x32_bf16 v[10:13], v[194:197], v[218:221], v[10:13]
	v_mfma_f32_16x16x32_bf16 v[6:9], v[186:189], v[226:229], v[6:9]
	v_mfma_f32_16x16x32_bf16 v[2:5], v[194:197], v[226:229], v[2:5]
	s_setprio 0
	s_barrier
	s_add_i32 s58, s58, 2
	s_add_u32 s28, s28, 0x100
	s_addc_u32 s29, s29, 0
	s_add_u32 s56, s56, 0x100
	s_addc_u32 s57, s57, 0
	s_cmp_gt_u32 s58, 29
	s_cbranch_scc0 .LBB0_568
	s_and_b64 vcc, exec, s[14:15]
	s_cbranch_vccz .LBB0_571
	s_barrier

.LBB0_623:
	s_add_u32 s38, s36, 0xfff80080
	s_addc_u32 s39, s37, -1
	s_cmp_eq_u32 s64, 28
	s_cselect_b32 s41, s25, s39
	s_cselect_b32 s40, s60, s38
	s_cselect_b32 s39, s27, s63
	s_cselect_b32 s38, s61, s62
	v_lshl_add_u64 v[148:149], s[36:37], 0, v[140:141]
	s_add_i32 m0, s35, 0xc000
	s_nop 0
	global_load_lds_dwordx4 v[148:149], off
	v_lshl_add_u64 v[148:149], s[36:37], 0, v[142:143]
	s_add_i32 m0, s35, 0xe000
	s_nop 0
	global_load_lds_dwordx4 v[148:149], off
	ds_read_b128 v[158:161], v1
	ds_read_b128 v[162:165], v1 offset:1024
	ds_read_b128 v[166:169], v1 offset:2048
	ds_read_b128 v[170:173], v1 offset:3072
	ds_read_b128 v[174:177], v155
	ds_read_b128 v[178:181], v155 offset:1024
	ds_read_b128 v[182:185], v155 offset:2048
	ds_read_b128 v[186:189], v155 offset:3072
	ds_read_b128 v[190:193], v156
	ds_read_b128 v[194:197], v156 offset:1024
	ds_read_b128 v[198:201], v156 offset:2048
	ds_read_b128 v[202:205], v156 offset:3072
	ds_read_b128 v[206:209], v156 offset:4096
	ds_read_b128 v[210:213], v156 offset:5120
	ds_read_b128 v[214:217], v156 offset:6144
	ds_read_b128 v[218:221], v156 offset:7168
	s_waitcnt vmcnt(8)
	s_waitcnt lgkmcnt(0)
	s_barrier
	s_setprio 1
	s_waitcnt lgkmcnt(0)
	v_mfma_f32_16x16x32_bf16 v[126:129], v[158:161], v[190:193], v[126:129]
	v_mfma_f32_16x16x32_bf16 v[122:125], v[166:169], v[190:193], v[122:125]
	v_mfma_f32_16x16x32_bf16 v[118:121], v[158:161], v[198:201], v[118:121]
	v_mfma_f32_16x16x32_bf16 v[110:113], v[166:169], v[198:201], v[110:113]
	v_mfma_f32_16x16x32_bf16 v[102:105], v[158:161], v[206:209], v[102:105]
	v_mfma_f32_16x16x32_bf16 v[94:97], v[166:169], v[206:209], v[94:97]
	v_mfma_f32_16x16x32_bf16 v[86:89], v[158:161], v[214:217], v[86:89]
	v_mfma_f32_16x16x32_bf16 v[78:81], v[166:169], v[214:217], v[78:81]
	v_mfma_f32_16x16x32_bf16 v[126:129], v[162:165], v[194:197], v[126:129]
	v_mfma_f32_16x16x32_bf16 v[122:125], v[170:173], v[194:197], v[122:125]
	v_mfma_f32_16x16x32_bf16 v[118:121], v[162:165], v[202:205], v[118:121]
	v_mfma_f32_16x16x32_bf16 v[110:113], v[170:173], v[202:205], v[110:113]
	v_mfma_f32_16x16x32_bf16 v[102:105], v[162:165], v[210:213], v[102:105]
	v_mfma_f32_16x16x32_bf16 v[94:97], v[170:173], v[210:213], v[94:97]
	v_mfma_f32_16x16x32_bf16 v[86:89], v[162:165], v[218:221], v[86:89]
	v_mfma_f32_16x16x32_bf16 v[78:81], v[170:173], v[218:221], v[78:81]
	s_setprio 0
	s_setprio 1
	v_mfma_f32_16x16x32_bf16 v[114:117], v[174:177], v[190:193], v[114:117]
	v_mfma_f32_16x16x32_bf16 v[106:109], v[182:185], v[190:193], v[106:109]
	v_mfma_f32_16x16x32_bf16 v[98:101], v[174:177], v[198:201], v[98:101]
	v_mfma_f32_16x16x32_bf16 v[90:93], v[182:185], v[198:201], v[90:93]
	v_mfma_f32_16x16x32_bf16 v[82:85], v[174:177], v[206:209], v[82:85]
	v_mfma_f32_16x16x32_bf16 v[74:77], v[182:185], v[206:209], v[74:77]
	v_mfma_f32_16x16x32_bf16 v[70:73], v[174:177], v[214:217], v[70:73]
	v_mfma_f32_16x16x32_bf16 v[66:69], v[182:185], v[214:217], v[66:69]
	v_mfma_f32_16x16x32_bf16 v[114:117], v[178:181], v[194:197], v[114:117]
	v_mfma_f32_16x16x32_bf16 v[106:109], v[186:189], v[194:197], v[106:109]
	v_mfma_f32_16x16x32_bf16 v[98:101], v[178:181], v[202:205], v[98:101]
	v_mfma_f32_16x16x32_bf16 v[90:93], v[186:189], v[202:205], v[90:93]
	v_mfma_f32_16x16x32_bf16 v[82:85], v[178:181], v[210:213], v[82:85]
	v_mfma_f32_16x16x32_bf16 v[74:77], v[186:189], v[210:213], v[74:77]
	v_mfma_f32_16x16x32_bf16 v[70:73], v[178:181], v[218:221], v[70:73]
	v_mfma_f32_16x16x32_bf16 v[66:69], v[186:189], v[218:221], v[66:69]
	s_setprio 0
	s_barrier
	s_add_i32 s65, s54, s46
	v_lshl_add_u64 v[148:149], s[38:39], 0, v[134:135]
	s_mov_b32 m0, s65
	s_nop 0
	global_load_lds_dwordx4 v[148:149], off
	s_add_i32 m0, s65, 0x2000
	s_add_u32 s66, s38, 0x80000
	v_lshl_add_u64 v[222:223], s[38:39], 0, v[138:139]
	s_addc_u32 s67, s39, 0
	s_add_i32 s65, s55, s46
	global_load_lds_dwordx4 v[222:223], off
	v_lshl_add_u64 v[224:225], s[66:67], 0, v[134:135]
	s_mov_b32 m0, s65
	v_lshl_add_u64 v[226:227], s[40:41], 0, v[136:137]
	global_load_lds_dwordx4 v[224:225], off
	v_lshl_add_u64 v[224:225], s[66:67], 0, v[138:139]
	s_add_i32 m0, s65, 0x2000
	s_nop 0
	global_load_lds_dwordx4 v[224:225], off
	v_lshl_add_u64 v[224:225], s[40:41], 0, v[132:133]
	s_mov_b32 m0, s35
	s_nop 0
	global_load_lds_dwordx4 v[224:225], off
	s_mov_b32 m0, s47
	s_nop 0
	global_load_lds_dwordx4 v[226:227], off
	ds_read_b128 v[190:193], v156 offset:16384
	ds_read_b128 v[194:197], v156 offset:17408
	ds_read_b128 v[198:201], v156 offset:18432
	ds_read_b128 v[202:205], v156 offset:19456
	ds_read_b128 v[206:209], v156 offset:20480
	ds_read_b128 v[210:213], v156 offset:21504
	ds_read_b128 v[214:217], v156 offset:22528
	ds_read_b128 v[218:221], v156 offset:23552
	s_waitcnt vmcnt(8)
	s_waitcnt lgkmcnt(0)
	s_barrier
	s_setprio 1
	s_waitcnt lgkmcnt(0)
	v_mfma_f32_16x16x32_bf16 v[62:65], v[158:161], v[190:193], v[62:65]
	v_mfma_f32_16x16x32_bf16 v[58:61], v[166:169], v[190:193], v[58:61]
	v_mfma_f32_16x16x32_bf16 v[54:57], v[158:161], v[198:201], v[54:57]
	v_mfma_f32_16x16x32_bf16 v[46:49], v[166:169], v[198:201], v[46:49]
	v_mfma_f32_16x16x32_bf16 v[38:41], v[158:161], v[206:209], v[38:41]
	v_mfma_f32_16x16x32_bf16 v[30:33], v[166:169], v[206:209], v[30:33]
	v_mfma_f32_16x16x32_bf16 v[22:25], v[158:161], v[214:217], v[22:25]
	v_mfma_f32_16x16x32_bf16 v[14:17], v[166:169], v[214:217], v[14:17]
	v_mfma_f32_16x16x32_bf16 v[62:65], v[162:165], v[194:197], v[62:65]
	v_mfma_f32_16x16x32_bf16 v[58:61], v[170:173], v[194:197], v[58:61]
	v_mfma_f32_16x16x32_bf16 v[54:57], v[162:165], v[202:205], v[54:57]
	v_mfma_f32_16x16x32_bf16 v[46:49], v[170:173], v[202:205], v[46:49]
	v_mfma_f32_16x16x32_bf16 v[38:41], v[162:165], v[210:213], v[38:41]
	v_mfma_f32_16x16x32_bf16 v[30:33], v[170:173], v[210:213], v[30:33]
	v_mfma_f32_16x16x32_bf16 v[22:25], v[162:165], v[218:221], v[22:25]
	v_mfma_f32_16x16x32_bf16 v[14:17], v[170:173], v[218:221], v[14:17]
	s_setprio 0
	s_setprio 1
	v_mfma_f32_16x16x32_bf16 v[50:53], v[174:177], v[190:193], v[50:53]
	v_mfma_f32_16x16x32_bf16 v[42:45], v[182:185], v[190:193], v[42:45]
	v_mfma_f32_16x16x32_bf16 v[34:37], v[174:177], v[198:201], v[34:37]
	v_mfma_f32_16x16x32_bf16 v[26:29], v[182:185], v[198:201], v[26:29]
	v_mfma_f32_16x16x32_bf16 v[18:21], v[174:177], v[206:209], v[18:21]
	v_mfma_f32_16x16x32_bf16 v[10:13], v[182:185], v[206:209], v[10:13]
	v_mfma_f32_16x16x32_bf16 v[6:9], v[174:177], v[214:217], v[6:9]
	v_mfma_f32_16x16x32_bf16 v[2:5], v[182:185], v[214:217], v[2:5]
	v_mfma_f32_16x16x32_bf16 v[50:53], v[178:181], v[194:197], v[50:53]
	v_mfma_f32_16x16x32_bf16 v[42:45], v[186:189], v[194:197], v[42:45]
	v_mfma_f32_16x16x32_bf16 v[34:37], v[178:181], v[202:205], v[34:37]
	v_mfma_f32_16x16x32_bf16 v[26:29], v[186:189], v[202:205], v[26:29]
	v_mfma_f32_16x16x32_bf16 v[18:21], v[178:181], v[210:213], v[18:21]
	v_mfma_f32_16x16x32_bf16 v[10:13], v[186:189], v[210:213], v[10:13]
	v_mfma_f32_16x16x32_bf16 v[6:9], v[178:181], v[218:221], v[6:9]
	v_mfma_f32_16x16x32_bf16 v[2:5], v[186:189], v[218:221], v[2:5]
	s_setprio 0
	s_barrier
	s_add_i32 s65, 0, 0x18000
	s_add_i32 s66, 0, 0x1c000
	v_add_u32_e32 v170, s65, v151
	v_add_u32_e32 v186, s66, v151
	ds_read_b128 v[158:161], v170
	ds_read_b128 v[162:165], v170 offset:1024
	ds_read_b128 v[166:169], v170 offset:2048
	ds_read_b128 v[170:173], v170 offset:3072
	ds_read_b128 v[174:177], v186
	ds_read_b128 v[178:181], v186 offset:1024
	ds_read_b128 v[182:185], v186 offset:2048
	ds_read_b128 v[186:189], v186 offset:3072
	s_add_u32 s40, s40, 0x80000
	s_addc_u32 s41, s41, 0
	s_mov_b32 m0, s48
	v_lshl_add_u64 v[228:229], s[40:41], 0, v[132:133]
	ds_read_b128 v[190:193], v156 offset:32768
	ds_read_b128 v[194:197], v156 offset:33792
	ds_read_b128 v[198:201], v156 offset:34816
	ds_read_b128 v[202:205], v156 offset:35840
	ds_read_b128 v[206:209], v156 offset:36864
	ds_read_b128 v[210:213], v156 offset:37888
	ds_read_b128 v[214:217], v156 offset:38912
	ds_read_b128 v[218:221], v156 offset:39936
	global_load_lds_dwordx4 v[228:229], off
	v_lshl_add_u64 v[228:229], s[40:41], 0, v[136:137]
	s_mov_b32 m0, s49
	s_nop 0
	global_load_lds_dwordx4 v[228:229], off
	s_waitcnt vmcnt(8)
	s_waitcnt lgkmcnt(0)
	s_barrier
	s_setprio 1
	s_waitcnt lgkmcnt(0)
	v_mfma_f32_16x16x32_bf16 v[126:129], v[158:161], v[190:193], v[126:129]
	v_mfma_f32_16x16x32_bf16 v[122:125], v[166:169], v[190:193], v[122:125]
	v_mfma_f32_16x16x32_bf16 v[118:121], v[158:161], v[198:201], v[118:121]
	v_mfma_f32_16x16x32_bf16 v[110:113], v[166:169], v[198:201], v[110:113]
	v_mfma_f32_16x16x32_bf16 v[102:105], v[158:161], v[206:209], v[102:105]
	v_mfma_f32_16x16x32_bf16 v[94:97], v[166:169], v[206:209], v[94:97]
	v_mfma_f32_16x16x32_bf16 v[86:89], v[158:161], v[214:217], v[86:89]
	v_mfma_f32_16x16x32_bf16 v[78:81], v[166:169], v[214:217], v[78:81]
	v_mfma_f32_16x16x32_bf16 v[126:129], v[162:165], v[194:197], v[126:129]
	v_mfma_f32_16x16x32_bf16 v[122:125], v[170:173], v[194:197], v[122:125]
	v_mfma_f32_16x16x32_bf16 v[118:121], v[162:165], v[202:205], v[118:121]
	v_mfma_f32_16x16x32_bf16 v[110:113], v[170:173], v[202:205], v[110:113]
	v_mfma_f32_16x16x32_bf16 v[102:105], v[162:165], v[210:213], v[102:105]
	v_mfma_f32_16x16x32_bf16 v[94:97], v[170:173], v[210:213], v[94:97]
	v_mfma_f32_16x16x32_bf16 v[86:89], v[162:165], v[218:221], v[86:89]
	v_mfma_f32_16x16x32_bf16 v[78:81], v[170:173], v[218:221], v[78:81]
	s_setprio 0
	s_setprio 1
	v_mfma_f32_16x16x32_bf16 v[114:117], v[174:177], v[190:193], v[114:117]
	v_mfma_f32_16x16x32_bf16 v[106:109], v[182:185], v[190:193], v[106:109]
	v_mfma_f32_16x16x32_bf16 v[98:101], v[174:177], v[198:201], v[98:101]
	v_mfma_f32_16x16x32_bf16 v[90:93], v[182:185], v[198:201], v[90:93]
	v_mfma_f32_16x16x32_bf16 v[82:85], v[174:177], v[206:209], v[82:85]
	v_mfma_f32_16x16x32_bf16 v[74:77], v[182:185], v[206:209], v[74:77]
	v_mfma_f32_16x16x32_bf16 v[70:73], v[174:177], v[214:217], v[70:73]
	v_mfma_f32_16x16x32_bf16 v[66:69], v[182:185], v[214:217], v[66:69]
	v_mfma_f32_16x16x32_bf16 v[114:117], v[178:181], v[194:197], v[114:117]
	v_mfma_f32_16x16x32_bf16 v[106:109], v[186:189], v[194:197], v[106:109]
	v_mfma_f32_16x16x32_bf16 v[98:101], v[178:181], v[202:205], v[98:101]
	v_mfma_f32_16x16x32_bf16 v[90:93], v[186:189], v[202:205], v[90:93]
	v_mfma_f32_16x16x32_bf16 v[82:85], v[178:181], v[210:213], v[82:85]
	v_mfma_f32_16x16x32_bf16 v[74:77], v[186:189], v[210:213], v[74:77]
	v_mfma_f32_16x16x32_bf16 v[70:73], v[178:181], v[218:221], v[70:73]
	v_mfma_f32_16x16x32_bf16 v[66:69], v[186:189], v[218:221], v[66:69]
	s_setprio 0
	s_barrier
	s_add_i32 s40, s65, s46
	v_lshl_add_u64 v[148:149], v[148:149], 0, s[14:15]
	s_mov_b32 m0, s40
	s_nop 0
	global_load_lds_dwordx4 v[148:149], off
	s_add_i32 m0, s40, 0x2000
	s_add_u32 s38, s38, 0x80080
	v_lshl_add_u64 v[148:149], v[222:223], 0, s[14:15]
	s_addc_u32 s39, s39, 0
	s_add_i32 s40, s66, s46
	global_load_lds_dwordx4 v[148:149], off
	v_lshl_add_u64 v[148:149], s[38:39], 0, v[134:135]
	s_mov_b32 m0, s40
	s_nop 0
	global_load_lds_dwordx4 v[148:149], off
	v_lshl_add_u64 v[148:149], s[38:39], 0, v[138:139]
	s_add_i32 m0, s40, 0x2000
	s_nop 0
	global_load_lds_dwordx4 v[148:149], off
	v_lshl_add_u64 v[148:149], v[224:225], 0, s[14:15]
	s_mov_b32 m0, s52
	s_nop 0
	global_load_lds_dwordx4 v[148:149], off
	v_lshl_add_u64 v[148:149], v[226:227], 0, s[14:15]
	s_mov_b32 m0, s53
	s_nop 0
	global_load_lds_dwordx4 v[148:149], off
	ds_read_b128 v[190:193], v156 offset:49152
	ds_read_b128 v[194:197], v156 offset:50176
	ds_read_b128 v[198:201], v156 offset:51200
	ds_read_b128 v[202:205], v156 offset:52224
	ds_read_b128 v[206:209], v156 offset:53248
	ds_read_b128 v[210:213], v156 offset:54272
	ds_read_b128 v[214:217], v156 offset:55296
	ds_read_b128 v[218:221], v156 offset:56320
	s_waitcnt vmcnt(8)
	s_waitcnt lgkmcnt(0)
	s_barrier
	s_setprio 1
	s_waitcnt lgkmcnt(0)
	v_mfma_f32_16x16x32_bf16 v[62:65], v[158:161], v[190:193], v[62:65]
	v_mfma_f32_16x16x32_bf16 v[58:61], v[166:169], v[190:193], v[58:61]
	v_mfma_f32_16x16x32_bf16 v[54:57], v[158:161], v[198:201], v[54:57]
	v_mfma_f32_16x16x32_bf16 v[46:49], v[166:169], v[198:201], v[46:49]
	v_mfma_f32_16x16x32_bf16 v[38:41], v[158:161], v[206:209], v[38:41]
	v_mfma_f32_16x16x32_bf16 v[30:33], v[166:169], v[206:209], v[30:33]
	v_mfma_f32_16x16x32_bf16 v[22:25], v[158:161], v[214:217], v[22:25]
	v_mfma_f32_16x16x32_bf16 v[14:17], v[166:169], v[214:217], v[14:17]
	v_mfma_f32_16x16x32_bf16 v[62:65], v[162:165], v[194:197], v[62:65]
	v_mfma_f32_16x16x32_bf16 v[58:61], v[170:173], v[194:197], v[58:61]
	v_mfma_f32_16x16x32_bf16 v[54:57], v[162:165], v[202:205], v[54:57]
	v_mfma_f32_16x16x32_bf16 v[46:49], v[170:173], v[202:205], v[46:49]
	v_mfma_f32_16x16x32_bf16 v[38:41], v[162:165], v[210:213], v[38:41]
	v_mfma_f32_16x16x32_bf16 v[30:33], v[170:173], v[210:213], v[30:33]
	v_mfma_f32_16x16x32_bf16 v[22:25], v[162:165], v[218:221], v[22:25]
	v_mfma_f32_16x16x32_bf16 v[14:17], v[170:173], v[218:221], v[14:17]
	s_setprio 0
	s_setprio 1
	v_mfma_f32_16x16x32_bf16 v[50:53], v[174:177], v[190:193], v[50:53]
	v_mfma_f32_16x16x32_bf16 v[42:45], v[182:185], v[190:193], v[42:45]
	v_mfma_f32_16x16x32_bf16 v[34:37], v[174:177], v[198:201], v[34:37]
	v_mfma_f32_16x16x32_bf16 v[26:29], v[182:185], v[198:201], v[26:29]
	v_mfma_f32_16x16x32_bf16 v[18:21], v[174:177], v[206:209], v[18:21]
	v_mfma_f32_16x16x32_bf16 v[10:13], v[182:185], v[206:209], v[10:13]
	v_mfma_f32_16x16x32_bf16 v[6:9], v[174:177], v[214:217], v[6:9]
	v_mfma_f32_16x16x32_bf16 v[2:5], v[182:185], v[214:217], v[2:5]
	v_mfma_f32_16x16x32_bf16 v[50:53], v[178:181], v[194:197], v[50:53]
	v_mfma_f32_16x16x32_bf16 v[42:45], v[186:189], v[194:197], v[42:45]
	v_mfma_f32_16x16x32_bf16 v[34:37], v[178:181], v[202:205], v[34:37]
	v_mfma_f32_16x16x32_bf16 v[26:29], v[186:189], v[202:205], v[26:29]
	v_mfma_f32_16x16x32_bf16 v[18:21], v[178:181], v[210:213], v[18:21]
	v_mfma_f32_16x16x32_bf16 v[10:13], v[186:189], v[210:213], v[10:13]
	v_mfma_f32_16x16x32_bf16 v[6:9], v[178:181], v[218:221], v[6:9]
	v_mfma_f32_16x16x32_bf16 v[2:5], v[186:189], v[218:221], v[2:5]
	s_setprio 0
	s_barrier
	s_add_i32 s64, s64, 2
	s_add_u32 s36, s36, 0x100
	s_addc_u32 s37, s37, 0
	s_add_u32 s62, s62, 0x100
	s_addc_u32 s63, s63, 0
	s_cmp_gt_u32 s64, 29
	s_cbranch_scc0 .LBB0_623
	s_and_b64 vcc, exec, s[16:17]
	s_cbranch_vccz .LBB0_626
	s_barrier

.LBB0_887:
	s_add_u32 s36, s34, 0xfff80080
	s_addc_u32 s37, s35, -1
	s_cmp_eq_u32 s63, 28
	s_cselect_b32 s39, s25, s37
	s_cselect_b32 s38, s59, s36
	s_cselect_b32 s37, s23, s62
	s_cselect_b32 s36, s60, s61
	v_lshl_add_u64 v[146:147], s[34:35], 0, v[138:139]
	s_add_i32 m0, s31, 0xc000
	s_nop 0
	global_load_lds_dwordx4 v[146:147], off
	v_lshl_add_u64 v[146:147], s[34:35], 0, v[140:141]
	s_add_i32 m0, s31, 0xe000
	s_nop 0
	global_load_lds_dwordx4 v[146:147], off
	ds_read_b128 v[156:159], v151
	ds_read_b128 v[160:163], v151 offset:1024
	ds_read_b128 v[164:167], v151 offset:2048
	ds_read_b128 v[168:171], v151 offset:3072
	ds_read_b128 v[172:175], v154
	ds_read_b128 v[176:179], v154 offset:1024
	ds_read_b128 v[180:183], v154 offset:2048
	ds_read_b128 v[184:187], v154 offset:3072
	ds_read_b128 v[188:191], v155
	ds_read_b128 v[192:195], v155 offset:1024
	ds_read_b128 v[196:199], v155 offset:2048
	ds_read_b128 v[200:203], v155 offset:3072
	ds_read_b128 v[204:207], v155 offset:4096
	ds_read_b128 v[208:211], v155 offset:5120
	ds_read_b128 v[212:215], v155 offset:6144
	ds_read_b128 v[216:219], v155 offset:7168
	s_waitcnt vmcnt(8)
	s_waitcnt lgkmcnt(0)
	s_barrier
	s_setprio 1
	s_waitcnt lgkmcnt(0)
	v_mfma_f32_16x16x32_bf16 v[126:129], v[156:159], v[188:191], v[126:129]
	v_mfma_f32_16x16x32_bf16 v[122:125], v[164:167], v[188:191], v[122:125]
	v_mfma_f32_16x16x32_bf16 v[118:121], v[156:159], v[196:199], v[118:121]
	v_mfma_f32_16x16x32_bf16 v[110:113], v[164:167], v[196:199], v[110:113]
	v_mfma_f32_16x16x32_bf16 v[102:105], v[156:159], v[204:207], v[102:105]
	v_mfma_f32_16x16x32_bf16 v[94:97], v[164:167], v[204:207], v[94:97]
	v_mfma_f32_16x16x32_bf16 v[86:89], v[156:159], v[212:215], v[86:89]
	v_mfma_f32_16x16x32_bf16 v[78:81], v[164:167], v[212:215], v[78:81]
	v_mfma_f32_16x16x32_bf16 v[126:129], v[160:163], v[192:195], v[126:129]
	v_mfma_f32_16x16x32_bf16 v[122:125], v[168:171], v[192:195], v[122:125]
	v_mfma_f32_16x16x32_bf16 v[118:121], v[160:163], v[200:203], v[118:121]
	v_mfma_f32_16x16x32_bf16 v[110:113], v[168:171], v[200:203], v[110:113]
	v_mfma_f32_16x16x32_bf16 v[102:105], v[160:163], v[208:211], v[102:105]
	v_mfma_f32_16x16x32_bf16 v[94:97], v[168:171], v[208:211], v[94:97]
	v_mfma_f32_16x16x32_bf16 v[86:89], v[160:163], v[216:219], v[86:89]
	v_mfma_f32_16x16x32_bf16 v[78:81], v[168:171], v[216:219], v[78:81]
	s_setprio 0
	s_setprio 1
	v_mfma_f32_16x16x32_bf16 v[114:117], v[172:175], v[188:191], v[114:117]
	v_mfma_f32_16x16x32_bf16 v[106:109], v[180:183], v[188:191], v[106:109]
	v_mfma_f32_16x16x32_bf16 v[98:101], v[172:175], v[196:199], v[98:101]
	v_mfma_f32_16x16x32_bf16 v[90:93], v[180:183], v[196:199], v[90:93]
	v_mfma_f32_16x16x32_bf16 v[82:85], v[172:175], v[204:207], v[82:85]
	v_mfma_f32_16x16x32_bf16 v[74:77], v[180:183], v[204:207], v[74:77]
	v_mfma_f32_16x16x32_bf16 v[70:73], v[172:175], v[212:215], v[70:73]
	v_mfma_f32_16x16x32_bf16 v[66:69], v[180:183], v[212:215], v[66:69]
	v_mfma_f32_16x16x32_bf16 v[114:117], v[176:179], v[192:195], v[114:117]
	v_mfma_f32_16x16x32_bf16 v[106:109], v[184:187], v[192:195], v[106:109]
	v_mfma_f32_16x16x32_bf16 v[98:101], v[176:179], v[200:203], v[98:101]
	v_mfma_f32_16x16x32_bf16 v[90:93], v[184:187], v[200:203], v[90:93]
	v_mfma_f32_16x16x32_bf16 v[82:85], v[176:179], v[208:211], v[82:85]
	v_mfma_f32_16x16x32_bf16 v[74:77], v[184:187], v[208:211], v[74:77]
	v_mfma_f32_16x16x32_bf16 v[70:73], v[176:179], v[216:219], v[70:73]
	v_mfma_f32_16x16x32_bf16 v[66:69], v[184:187], v[216:219], v[66:69]
	s_setprio 0
	s_barrier
	s_add_i32 s64, s52, s44
	v_lshl_add_u64 v[146:147], s[36:37], 0, v[132:133]
	s_mov_b32 m0, s64
	s_nop 0
	global_load_lds_dwordx4 v[146:147], off
	s_add_i32 m0, s64, 0x2000
	s_add_u32 s64, s36, 0x80000
	v_lshl_add_u64 v[220:221], s[36:37], 0, v[136:137]
	s_addc_u32 s65, s37, 0
	s_add_i32 s66, s53, s44
	global_load_lds_dwordx4 v[220:221], off
	v_lshl_add_u64 v[222:223], s[64:65], 0, v[132:133]
	s_mov_b32 m0, s66
	v_lshl_add_u64 v[224:225], s[38:39], 0, v[134:135]
	global_load_lds_dwordx4 v[222:223], off
	v_lshl_add_u64 v[222:223], s[64:65], 0, v[136:137]
	s_add_i32 m0, s66, 0x2000
	s_nop 0
	global_load_lds_dwordx4 v[222:223], off
	v_lshl_add_u64 v[222:223], s[38:39], 0, v[130:131]
	s_mov_b32 m0, s31
	s_nop 0
	global_load_lds_dwordx4 v[222:223], off
	s_mov_b32 m0, s45
	s_nop 0
	global_load_lds_dwordx4 v[224:225], off
	ds_read_b128 v[188:191], v155 offset:16384
	ds_read_b128 v[192:195], v155 offset:17408
	ds_read_b128 v[196:199], v155 offset:18432
	ds_read_b128 v[200:203], v155 offset:19456
	ds_read_b128 v[204:207], v155 offset:20480
	ds_read_b128 v[208:211], v155 offset:21504
	ds_read_b128 v[212:215], v155 offset:22528
	ds_read_b128 v[216:219], v155 offset:23552
	s_waitcnt vmcnt(8)
	s_waitcnt lgkmcnt(0)
	s_barrier
	s_setprio 1
	s_waitcnt lgkmcnt(0)
	v_mfma_f32_16x16x32_bf16 v[62:65], v[156:159], v[188:191], v[62:65]
	v_mfma_f32_16x16x32_bf16 v[58:61], v[164:167], v[188:191], v[58:61]
	v_mfma_f32_16x16x32_bf16 v[54:57], v[156:159], v[196:199], v[54:57]
	v_mfma_f32_16x16x32_bf16 v[46:49], v[164:167], v[196:199], v[46:49]
	v_mfma_f32_16x16x32_bf16 v[38:41], v[156:159], v[204:207], v[38:41]
	v_mfma_f32_16x16x32_bf16 v[30:33], v[164:167], v[204:207], v[30:33]
	v_mfma_f32_16x16x32_bf16 v[22:25], v[156:159], v[212:215], v[22:25]
	v_mfma_f32_16x16x32_bf16 v[14:17], v[164:167], v[212:215], v[14:17]
	v_mfma_f32_16x16x32_bf16 v[62:65], v[160:163], v[192:195], v[62:65]
	v_mfma_f32_16x16x32_bf16 v[58:61], v[168:171], v[192:195], v[58:61]
	v_mfma_f32_16x16x32_bf16 v[54:57], v[160:163], v[200:203], v[54:57]
	v_mfma_f32_16x16x32_bf16 v[46:49], v[168:171], v[200:203], v[46:49]
	v_mfma_f32_16x16x32_bf16 v[38:41], v[160:163], v[208:211], v[38:41]
	v_mfma_f32_16x16x32_bf16 v[30:33], v[168:171], v[208:211], v[30:33]
	v_mfma_f32_16x16x32_bf16 v[22:25], v[160:163], v[216:219], v[22:25]
	v_mfma_f32_16x16x32_bf16 v[14:17], v[168:171], v[216:219], v[14:17]
	s_setprio 0
	s_setprio 1
	v_mfma_f32_16x16x32_bf16 v[50:53], v[172:175], v[188:191], v[50:53]
	v_mfma_f32_16x16x32_bf16 v[42:45], v[180:183], v[188:191], v[42:45]
	v_mfma_f32_16x16x32_bf16 v[34:37], v[172:175], v[196:199], v[34:37]
	v_mfma_f32_16x16x32_bf16 v[26:29], v[180:183], v[196:199], v[26:29]
	v_mfma_f32_16x16x32_bf16 v[18:21], v[172:175], v[204:207], v[18:21]
	v_mfma_f32_16x16x32_bf16 v[10:13], v[180:183], v[204:207], v[10:13]
	v_mfma_f32_16x16x32_bf16 v[6:9], v[172:175], v[212:215], v[6:9]
	v_mfma_f32_16x16x32_bf16 v[2:5], v[180:183], v[212:215], v[2:5]
	v_mfma_f32_16x16x32_bf16 v[50:53], v[176:179], v[192:195], v[50:53]
	v_mfma_f32_16x16x32_bf16 v[42:45], v[184:187], v[192:195], v[42:45]
	v_mfma_f32_16x16x32_bf16 v[34:37], v[176:179], v[200:203], v[34:37]
	v_mfma_f32_16x16x32_bf16 v[26:29], v[184:187], v[200:203], v[26:29]
	v_mfma_f32_16x16x32_bf16 v[18:21], v[176:179], v[208:211], v[18:21]
	v_mfma_f32_16x16x32_bf16 v[10:13], v[184:187], v[208:211], v[10:13]
	v_mfma_f32_16x16x32_bf16 v[6:9], v[176:179], v[216:219], v[6:9]
	v_mfma_f32_16x16x32_bf16 v[2:5], v[184:187], v[216:219], v[2:5]
	s_setprio 0
	s_barrier
	s_add_i32 s64, 0, 0x18000
	s_add_i32 s65, 0, 0x1c000
	v_add_u32_e32 v168, s64, v149
	v_add_u32_e32 v184, s65, v149
	ds_read_b128 v[156:159], v168
	ds_read_b128 v[160:163], v168 offset:1024
	ds_read_b128 v[164:167], v168 offset:2048
	ds_read_b128 v[168:171], v168 offset:3072
	ds_read_b128 v[172:175], v184
	ds_read_b128 v[176:179], v184 offset:1024
	ds_read_b128 v[180:183], v184 offset:2048
	ds_read_b128 v[184:187], v184 offset:3072
	s_add_u32 s38, s38, 0x80000
	s_addc_u32 s39, s39, 0
	s_mov_b32 m0, s46
	v_lshl_add_u64 v[226:227], s[38:39], 0, v[130:131]
	ds_read_b128 v[188:191], v155 offset:32768
	ds_read_b128 v[192:195], v155 offset:33792
	ds_read_b128 v[196:199], v155 offset:34816
	ds_read_b128 v[200:203], v155 offset:35840
	ds_read_b128 v[204:207], v155 offset:36864
	ds_read_b128 v[208:211], v155 offset:37888
	ds_read_b128 v[212:215], v155 offset:38912
	ds_read_b128 v[216:219], v155 offset:39936
	global_load_lds_dwordx4 v[226:227], off
	v_lshl_add_u64 v[226:227], s[38:39], 0, v[134:135]
	s_mov_b32 m0, s47
	s_nop 0
	global_load_lds_dwordx4 v[226:227], off
	s_waitcnt vmcnt(8)
	s_waitcnt lgkmcnt(0)
	s_barrier
	s_setprio 1
	s_waitcnt lgkmcnt(0)
	v_mfma_f32_16x16x32_bf16 v[126:129], v[156:159], v[188:191], v[126:129]
	v_mfma_f32_16x16x32_bf16 v[122:125], v[164:167], v[188:191], v[122:125]
	v_mfma_f32_16x16x32_bf16 v[118:121], v[156:159], v[196:199], v[118:121]
	v_mfma_f32_16x16x32_bf16 v[110:113], v[164:167], v[196:199], v[110:113]
	v_mfma_f32_16x16x32_bf16 v[102:105], v[156:159], v[204:207], v[102:105]
	v_mfma_f32_16x16x32_bf16 v[94:97], v[164:167], v[204:207], v[94:97]
	v_mfma_f32_16x16x32_bf16 v[86:89], v[156:159], v[212:215], v[86:89]
	v_mfma_f32_16x16x32_bf16 v[78:81], v[164:167], v[212:215], v[78:81]
	v_mfma_f32_16x16x32_bf16 v[126:129], v[160:163], v[192:195], v[126:129]
	v_mfma_f32_16x16x32_bf16 v[122:125], v[168:171], v[192:195], v[122:125]
	v_mfma_f32_16x16x32_bf16 v[118:121], v[160:163], v[200:203], v[118:121]
	v_mfma_f32_16x16x32_bf16 v[110:113], v[168:171], v[200:203], v[110:113]
	v_mfma_f32_16x16x32_bf16 v[102:105], v[160:163], v[208:211], v[102:105]
	v_mfma_f32_16x16x32_bf16 v[94:97], v[168:171], v[208:211], v[94:97]
	v_mfma_f32_16x16x32_bf16 v[86:89], v[160:163], v[216:219], v[86:89]
	v_mfma_f32_16x16x32_bf16 v[78:81], v[168:171], v[216:219], v[78:81]
	s_setprio 0
	s_setprio 1
	v_mfma_f32_16x16x32_bf16 v[114:117], v[172:175], v[188:191], v[114:117]
	v_mfma_f32_16x16x32_bf16 v[106:109], v[180:183], v[188:191], v[106:109]
	v_mfma_f32_16x16x32_bf16 v[98:101], v[172:175], v[196:199], v[98:101]
	v_mfma_f32_16x16x32_bf16 v[90:93], v[180:183], v[196:199], v[90:93]
	v_mfma_f32_16x16x32_bf16 v[82:85], v[172:175], v[204:207], v[82:85]
	v_mfma_f32_16x16x32_bf16 v[74:77], v[180:183], v[204:207], v[74:77]
	v_mfma_f32_16x16x32_bf16 v[70:73], v[172:175], v[212:215], v[70:73]
	v_mfma_f32_16x16x32_bf16 v[66:69], v[180:183], v[212:215], v[66:69]
	v_mfma_f32_16x16x32_bf16 v[114:117], v[176:179], v[192:195], v[114:117]
	v_mfma_f32_16x16x32_bf16 v[106:109], v[184:187], v[192:195], v[106:109]
	v_mfma_f32_16x16x32_bf16 v[98:101], v[176:179], v[200:203], v[98:101]
	v_mfma_f32_16x16x32_bf16 v[90:93], v[184:187], v[200:203], v[90:93]
	v_mfma_f32_16x16x32_bf16 v[82:85], v[176:179], v[208:211], v[82:85]
	v_mfma_f32_16x16x32_bf16 v[74:77], v[184:187], v[208:211], v[74:77]
	v_mfma_f32_16x16x32_bf16 v[70:73], v[176:179], v[216:219], v[70:73]
	v_mfma_f32_16x16x32_bf16 v[66:69], v[184:187], v[216:219], v[66:69]
	s_setprio 0
	s_barrier
	s_add_i32 s38, s64, s44
	v_lshl_add_u64 v[146:147], v[146:147], 0, s[12:13]
	s_mov_b32 m0, s38
	s_nop 0
	global_load_lds_dwordx4 v[146:147], off
	s_add_i32 m0, s38, 0x2000
	s_add_u32 s36, s36, 0x80080
	v_lshl_add_u64 v[146:147], v[220:221], 0, s[12:13]
	s_addc_u32 s37, s37, 0
	s_add_i32 s38, s65, s44
	global_load_lds_dwordx4 v[146:147], off
	v_lshl_add_u64 v[146:147], s[36:37], 0, v[132:133]
	s_mov_b32 m0, s38
	s_nop 0
	global_load_lds_dwordx4 v[146:147], off
	v_lshl_add_u64 v[146:147], s[36:37], 0, v[136:137]
	s_add_i32 m0, s38, 0x2000
	s_nop 0
	global_load_lds_dwordx4 v[146:147], off
	v_lshl_add_u64 v[146:147], v[222:223], 0, s[12:13]
	s_mov_b32 m0, s49
	s_nop 0
	global_load_lds_dwordx4 v[146:147], off
	v_lshl_add_u64 v[146:147], v[224:225], 0, s[12:13]
	s_mov_b32 m0, s50
	s_nop 0
	global_load_lds_dwordx4 v[146:147], off
	ds_read_b128 v[188:191], v155 offset:49152
	ds_read_b128 v[192:195], v155 offset:50176
	ds_read_b128 v[196:199], v155 offset:51200
	ds_read_b128 v[200:203], v155 offset:52224
	ds_read_b128 v[204:207], v155 offset:53248
	ds_read_b128 v[208:211], v155 offset:54272
	ds_read_b128 v[212:215], v155 offset:55296
	ds_read_b128 v[216:219], v155 offset:56320
	s_waitcnt vmcnt(8)
	s_waitcnt lgkmcnt(0)
	s_barrier
	s_setprio 1
	s_waitcnt lgkmcnt(0)
	v_mfma_f32_16x16x32_bf16 v[62:65], v[156:159], v[188:191], v[62:65]
	v_mfma_f32_16x16x32_bf16 v[58:61], v[164:167], v[188:191], v[58:61]
	v_mfma_f32_16x16x32_bf16 v[54:57], v[156:159], v[196:199], v[54:57]
	v_mfma_f32_16x16x32_bf16 v[46:49], v[164:167], v[196:199], v[46:49]
	v_mfma_f32_16x16x32_bf16 v[38:41], v[156:159], v[204:207], v[38:41]
	v_mfma_f32_16x16x32_bf16 v[30:33], v[164:167], v[204:207], v[30:33]
	v_mfma_f32_16x16x32_bf16 v[22:25], v[156:159], v[212:215], v[22:25]
	v_mfma_f32_16x16x32_bf16 v[14:17], v[164:167], v[212:215], v[14:17]
	v_mfma_f32_16x16x32_bf16 v[62:65], v[160:163], v[192:195], v[62:65]
	v_mfma_f32_16x16x32_bf16 v[58:61], v[168:171], v[192:195], v[58:61]
	v_mfma_f32_16x16x32_bf16 v[54:57], v[160:163], v[200:203], v[54:57]
	v_mfma_f32_16x16x32_bf16 v[46:49], v[168:171], v[200:203], v[46:49]
	v_mfma_f32_16x16x32_bf16 v[38:41], v[160:163], v[208:211], v[38:41]
	v_mfma_f32_16x16x32_bf16 v[30:33], v[168:171], v[208:211], v[30:33]
	v_mfma_f32_16x16x32_bf16 v[22:25], v[160:163], v[216:219], v[22:25]
	v_mfma_f32_16x16x32_bf16 v[14:17], v[168:171], v[216:219], v[14:17]
	s_setprio 0
	s_setprio 1
	v_mfma_f32_16x16x32_bf16 v[50:53], v[172:175], v[188:191], v[50:53]
	v_mfma_f32_16x16x32_bf16 v[42:45], v[180:183], v[188:191], v[42:45]
	v_mfma_f32_16x16x32_bf16 v[34:37], v[172:175], v[196:199], v[34:37]
	v_mfma_f32_16x16x32_bf16 v[26:29], v[180:183], v[196:199], v[26:29]
	v_mfma_f32_16x16x32_bf16 v[18:21], v[172:175], v[204:207], v[18:21]
	v_mfma_f32_16x16x32_bf16 v[10:13], v[180:183], v[204:207], v[10:13]
	v_mfma_f32_16x16x32_bf16 v[6:9], v[172:175], v[212:215], v[6:9]
	v_mfma_f32_16x16x32_bf16 v[2:5], v[180:183], v[212:215], v[2:5]
	v_mfma_f32_16x16x32_bf16 v[50:53], v[176:179], v[192:195], v[50:53]
	v_mfma_f32_16x16x32_bf16 v[42:45], v[184:187], v[192:195], v[42:45]
	v_mfma_f32_16x16x32_bf16 v[34:37], v[176:179], v[200:203], v[34:37]
	v_mfma_f32_16x16x32_bf16 v[26:29], v[184:187], v[200:203], v[26:29]
	v_mfma_f32_16x16x32_bf16 v[18:21], v[176:179], v[208:211], v[18:21]
	v_mfma_f32_16x16x32_bf16 v[10:13], v[184:187], v[208:211], v[10:13]
	v_mfma_f32_16x16x32_bf16 v[6:9], v[176:179], v[216:219], v[6:9]
	v_mfma_f32_16x16x32_bf16 v[2:5], v[184:187], v[216:219], v[2:5]
	s_setprio 0
	s_barrier
	s_add_i32 s63, s63, 2
	s_add_u32 s34, s34, 0x100
	s_addc_u32 s35, s35, 0
	s_add_u32 s61, s61, 0x100
	s_addc_u32 s62, s62, 0
	s_cmp_gt_u32 s63, 29
	s_cbranch_scc0 .LBB0_887
	s_and_b64 vcc, exec, s[14:15]
	s_cbranch_vccz .LBB0_890
	s_barrier

.LBB0_1082:
	s_add_u32 s36, s34, 0xfff80080
	s_addc_u32 s37, s35, -1
	s_cmp_eq_u32 s63, 28
	s_cselect_b32 s39, s25, s37
	s_cselect_b32 s38, s59, s36
	s_cselect_b32 s37, s23, s62
	s_cselect_b32 s36, s60, s61
	v_lshl_add_u64 v[146:147], s[34:35], 0, v[138:139]
	s_add_i32 m0, s31, 0xc000
	s_nop 0
	global_load_lds_dwordx4 v[146:147], off
	v_lshl_add_u64 v[146:147], s[34:35], 0, v[140:141]
	s_add_i32 m0, s31, 0xe000
	s_nop 0
	global_load_lds_dwordx4 v[146:147], off
	ds_read_b128 v[156:159], v151
	ds_read_b128 v[160:163], v151 offset:1024
	ds_read_b128 v[164:167], v151 offset:2048
	ds_read_b128 v[168:171], v151 offset:3072
	ds_read_b128 v[172:175], v154
	ds_read_b128 v[176:179], v154 offset:1024
	ds_read_b128 v[180:183], v154 offset:2048
	ds_read_b128 v[184:187], v154 offset:3072
	ds_read_b128 v[188:191], v155
	ds_read_b128 v[192:195], v155 offset:1024
	ds_read_b128 v[196:199], v155 offset:2048
	ds_read_b128 v[200:203], v155 offset:3072
	ds_read_b128 v[204:207], v155 offset:4096
	ds_read_b128 v[208:211], v155 offset:5120
	ds_read_b128 v[212:215], v155 offset:6144
	ds_read_b128 v[216:219], v155 offset:7168
	s_waitcnt vmcnt(8)
	s_waitcnt lgkmcnt(0)
	s_barrier
	s_setprio 1
	s_waitcnt lgkmcnt(0)
	v_mfma_f32_16x16x32_bf16 v[126:129], v[156:159], v[188:191], v[126:129]
	v_mfma_f32_16x16x32_bf16 v[122:125], v[164:167], v[188:191], v[122:125]
	v_mfma_f32_16x16x32_bf16 v[110:113], v[156:159], v[196:199], v[110:113]
	v_mfma_f32_16x16x32_bf16 v[106:109], v[164:167], v[196:199], v[106:109]
	v_mfma_f32_16x16x32_bf16 v[94:97], v[156:159], v[204:207], v[94:97]
	v_mfma_f32_16x16x32_bf16 v[90:93], v[164:167], v[204:207], v[90:93]
	v_mfma_f32_16x16x32_bf16 v[78:81], v[156:159], v[212:215], v[78:81]
	v_mfma_f32_16x16x32_bf16 v[74:77], v[164:167], v[212:215], v[74:77]
	v_mfma_f32_16x16x32_bf16 v[126:129], v[160:163], v[192:195], v[126:129]
	v_mfma_f32_16x16x32_bf16 v[122:125], v[168:171], v[192:195], v[122:125]
	v_mfma_f32_16x16x32_bf16 v[110:113], v[160:163], v[200:203], v[110:113]
	v_mfma_f32_16x16x32_bf16 v[106:109], v[168:171], v[200:203], v[106:109]
	v_mfma_f32_16x16x32_bf16 v[94:97], v[160:163], v[208:211], v[94:97]
	v_mfma_f32_16x16x32_bf16 v[90:93], v[168:171], v[208:211], v[90:93]
	v_mfma_f32_16x16x32_bf16 v[78:81], v[160:163], v[216:219], v[78:81]
	v_mfma_f32_16x16x32_bf16 v[74:77], v[168:171], v[216:219], v[74:77]
	s_setprio 0
	s_setprio 1
	v_mfma_f32_16x16x32_bf16 v[118:121], v[172:175], v[188:191], v[118:121]
	v_mfma_f32_16x16x32_bf16 v[114:117], v[180:183], v[188:191], v[114:117]
	v_mfma_f32_16x16x32_bf16 v[102:105], v[172:175], v[196:199], v[102:105]
	v_mfma_f32_16x16x32_bf16 v[98:101], v[180:183], v[196:199], v[98:101]
	v_mfma_f32_16x16x32_bf16 v[86:89], v[172:175], v[204:207], v[86:89]
	v_mfma_f32_16x16x32_bf16 v[82:85], v[180:183], v[204:207], v[82:85]
	v_mfma_f32_16x16x32_bf16 v[70:73], v[172:175], v[212:215], v[70:73]
	v_mfma_f32_16x16x32_bf16 v[66:69], v[180:183], v[212:215], v[66:69]
	v_mfma_f32_16x16x32_bf16 v[118:121], v[176:179], v[192:195], v[118:121]
	v_mfma_f32_16x16x32_bf16 v[114:117], v[184:187], v[192:195], v[114:117]
	v_mfma_f32_16x16x32_bf16 v[102:105], v[176:179], v[200:203], v[102:105]
	v_mfma_f32_16x16x32_bf16 v[98:101], v[184:187], v[200:203], v[98:101]
	v_mfma_f32_16x16x32_bf16 v[86:89], v[176:179], v[208:211], v[86:89]
	v_mfma_f32_16x16x32_bf16 v[82:85], v[184:187], v[208:211], v[82:85]
	v_mfma_f32_16x16x32_bf16 v[70:73], v[176:179], v[216:219], v[70:73]
	v_mfma_f32_16x16x32_bf16 v[66:69], v[184:187], v[216:219], v[66:69]
	s_setprio 0
	s_barrier
	s_add_i32 s64, s52, s44
	v_lshl_add_u64 v[146:147], s[36:37], 0, v[132:133]
	s_mov_b32 m0, s64
	s_nop 0
	global_load_lds_dwordx4 v[146:147], off
	s_add_i32 m0, s64, 0x2000
	s_add_u32 s64, s36, 0x80000
	v_lshl_add_u64 v[220:221], s[36:37], 0, v[136:137]
	s_addc_u32 s65, s37, 0
	s_add_i32 s66, s53, s44
	global_load_lds_dwordx4 v[220:221], off
	v_lshl_add_u64 v[222:223], s[64:65], 0, v[132:133]
	s_mov_b32 m0, s66
	v_lshl_add_u64 v[224:225], s[38:39], 0, v[134:135]
	global_load_lds_dwordx4 v[222:223], off
	v_lshl_add_u64 v[222:223], s[64:65], 0, v[136:137]
	s_add_i32 m0, s66, 0x2000
	s_nop 0
	global_load_lds_dwordx4 v[222:223], off
	v_lshl_add_u64 v[222:223], s[38:39], 0, v[130:131]
	s_mov_b32 m0, s31
	s_nop 0
	global_load_lds_dwordx4 v[222:223], off
	s_mov_b32 m0, s45
	s_nop 0
	global_load_lds_dwordx4 v[224:225], off
	ds_read_b128 v[188:191], v155 offset:16384
	ds_read_b128 v[192:195], v155 offset:17408
	ds_read_b128 v[196:199], v155 offset:18432
	ds_read_b128 v[200:203], v155 offset:19456
	ds_read_b128 v[204:207], v155 offset:20480
	ds_read_b128 v[208:211], v155 offset:21504
	ds_read_b128 v[212:215], v155 offset:22528
	ds_read_b128 v[216:219], v155 offset:23552
	s_waitcnt vmcnt(8)
	s_waitcnt lgkmcnt(0)
	s_barrier
	s_setprio 1
	s_waitcnt lgkmcnt(0)
	v_mfma_f32_16x16x32_bf16 v[62:65], v[156:159], v[188:191], v[62:65]
	v_mfma_f32_16x16x32_bf16 v[58:61], v[164:167], v[188:191], v[58:61]
	v_mfma_f32_16x16x32_bf16 v[46:49], v[156:159], v[196:199], v[46:49]
	v_mfma_f32_16x16x32_bf16 v[42:45], v[164:167], v[196:199], v[42:45]
	v_mfma_f32_16x16x32_bf16 v[30:33], v[156:159], v[204:207], v[30:33]
	v_mfma_f32_16x16x32_bf16 v[26:29], v[164:167], v[204:207], v[26:29]
	v_mfma_f32_16x16x32_bf16 v[14:17], v[156:159], v[212:215], v[14:17]
	v_mfma_f32_16x16x32_bf16 v[10:13], v[164:167], v[212:215], v[10:13]
	v_mfma_f32_16x16x32_bf16 v[62:65], v[160:163], v[192:195], v[62:65]
	v_mfma_f32_16x16x32_bf16 v[58:61], v[168:171], v[192:195], v[58:61]
	v_mfma_f32_16x16x32_bf16 v[46:49], v[160:163], v[200:203], v[46:49]
	v_mfma_f32_16x16x32_bf16 v[42:45], v[168:171], v[200:203], v[42:45]
	v_mfma_f32_16x16x32_bf16 v[30:33], v[160:163], v[208:211], v[30:33]
	v_mfma_f32_16x16x32_bf16 v[26:29], v[168:171], v[208:211], v[26:29]
	v_mfma_f32_16x16x32_bf16 v[14:17], v[160:163], v[216:219], v[14:17]
	v_mfma_f32_16x16x32_bf16 v[10:13], v[168:171], v[216:219], v[10:13]
	s_setprio 0
	s_setprio 1
	v_mfma_f32_16x16x32_bf16 v[54:57], v[172:175], v[188:191], v[54:57]
	v_mfma_f32_16x16x32_bf16 v[50:53], v[180:183], v[188:191], v[50:53]
	v_mfma_f32_16x16x32_bf16 v[38:41], v[172:175], v[196:199], v[38:41]
	v_mfma_f32_16x16x32_bf16 v[34:37], v[180:183], v[196:199], v[34:37]
	v_mfma_f32_16x16x32_bf16 v[22:25], v[172:175], v[204:207], v[22:25]
	v_mfma_f32_16x16x32_bf16 v[18:21], v[180:183], v[204:207], v[18:21]
	v_mfma_f32_16x16x32_bf16 v[6:9], v[172:175], v[212:215], v[6:9]
	v_mfma_f32_16x16x32_bf16 v[2:5], v[180:183], v[212:215], v[2:5]
	v_mfma_f32_16x16x32_bf16 v[54:57], v[176:179], v[192:195], v[54:57]
	v_mfma_f32_16x16x32_bf16 v[50:53], v[184:187], v[192:195], v[50:53]
	v_mfma_f32_16x16x32_bf16 v[38:41], v[176:179], v[200:203], v[38:41]
	v_mfma_f32_16x16x32_bf16 v[34:37], v[184:187], v[200:203], v[34:37]
	v_mfma_f32_16x16x32_bf16 v[22:25], v[176:179], v[208:211], v[22:25]
	v_mfma_f32_16x16x32_bf16 v[18:21], v[184:187], v[208:211], v[18:21]
	v_mfma_f32_16x16x32_bf16 v[6:9], v[176:179], v[216:219], v[6:9]
	v_mfma_f32_16x16x32_bf16 v[2:5], v[184:187], v[216:219], v[2:5]
	s_setprio 0
	s_barrier
	s_add_i32 s64, 0, 0x18000
	s_add_i32 s65, 0, 0x1c000
	v_add_u32_e32 v168, s64, v149
	v_add_u32_e32 v184, s65, v149
	ds_read_b128 v[156:159], v168
	ds_read_b128 v[160:163], v168 offset:1024
	ds_read_b128 v[164:167], v168 offset:2048
	ds_read_b128 v[168:171], v168 offset:3072
	ds_read_b128 v[172:175], v184
	ds_read_b128 v[176:179], v184 offset:1024
	ds_read_b128 v[180:183], v184 offset:2048
	ds_read_b128 v[184:187], v184 offset:3072
	s_add_u32 s38, s38, 0x80000
	s_addc_u32 s39, s39, 0
	s_mov_b32 m0, s46
	v_lshl_add_u64 v[226:227], s[38:39], 0, v[130:131]
	ds_read_b128 v[188:191], v155 offset:32768
	ds_read_b128 v[192:195], v155 offset:33792
	ds_read_b128 v[196:199], v155 offset:34816
	ds_read_b128 v[200:203], v155 offset:35840
	ds_read_b128 v[204:207], v155 offset:36864
	ds_read_b128 v[208:211], v155 offset:37888
	ds_read_b128 v[212:215], v155 offset:38912
	ds_read_b128 v[216:219], v155 offset:39936
	global_load_lds_dwordx4 v[226:227], off
	v_lshl_add_u64 v[226:227], s[38:39], 0, v[134:135]
	s_mov_b32 m0, s47
	s_nop 0
	global_load_lds_dwordx4 v[226:227], off
	s_waitcnt vmcnt(8)
	s_waitcnt lgkmcnt(0)
	s_barrier
	s_setprio 1
	s_waitcnt lgkmcnt(0)
	v_mfma_f32_16x16x32_bf16 v[126:129], v[156:159], v[188:191], v[126:129]
	v_mfma_f32_16x16x32_bf16 v[122:125], v[164:167], v[188:191], v[122:125]
	v_mfma_f32_16x16x32_bf16 v[110:113], v[156:159], v[196:199], v[110:113]
	v_mfma_f32_16x16x32_bf16 v[106:109], v[164:167], v[196:199], v[106:109]
	v_mfma_f32_16x16x32_bf16 v[94:97], v[156:159], v[204:207], v[94:97]
	v_mfma_f32_16x16x32_bf16 v[90:93], v[164:167], v[204:207], v[90:93]
	v_mfma_f32_16x16x32_bf16 v[78:81], v[156:159], v[212:215], v[78:81]
	v_mfma_f32_16x16x32_bf16 v[74:77], v[164:167], v[212:215], v[74:77]
	v_mfma_f32_16x16x32_bf16 v[126:129], v[160:163], v[192:195], v[126:129]
	v_mfma_f32_16x16x32_bf16 v[122:125], v[168:171], v[192:195], v[122:125]
	v_mfma_f32_16x16x32_bf16 v[110:113], v[160:163], v[200:203], v[110:113]
	v_mfma_f32_16x16x32_bf16 v[106:109], v[168:171], v[200:203], v[106:109]
	v_mfma_f32_16x16x32_bf16 v[94:97], v[160:163], v[208:211], v[94:97]
	v_mfma_f32_16x16x32_bf16 v[90:93], v[168:171], v[208:211], v[90:93]
	v_mfma_f32_16x16x32_bf16 v[78:81], v[160:163], v[216:219], v[78:81]
	v_mfma_f32_16x16x32_bf16 v[74:77], v[168:171], v[216:219], v[74:77]
	s_setprio 0
	s_setprio 1
	v_mfma_f32_16x16x32_bf16 v[118:121], v[172:175], v[188:191], v[118:121]
	v_mfma_f32_16x16x32_bf16 v[114:117], v[180:183], v[188:191], v[114:117]
	v_mfma_f32_16x16x32_bf16 v[102:105], v[172:175], v[196:199], v[102:105]
	v_mfma_f32_16x16x32_bf16 v[98:101], v[180:183], v[196:199], v[98:101]
	v_mfma_f32_16x16x32_bf16 v[86:89], v[172:175], v[204:207], v[86:89]
	v_mfma_f32_16x16x32_bf16 v[82:85], v[180:183], v[204:207], v[82:85]
	v_mfma_f32_16x16x32_bf16 v[70:73], v[172:175], v[212:215], v[70:73]
	v_mfma_f32_16x16x32_bf16 v[66:69], v[180:183], v[212:215], v[66:69]
	v_mfma_f32_16x16x32_bf16 v[118:121], v[176:179], v[192:195], v[118:121]
	v_mfma_f32_16x16x32_bf16 v[114:117], v[184:187], v[192:195], v[114:117]
	v_mfma_f32_16x16x32_bf16 v[102:105], v[176:179], v[200:203], v[102:105]
	v_mfma_f32_16x16x32_bf16 v[98:101], v[184:187], v[200:203], v[98:101]
	v_mfma_f32_16x16x32_bf16 v[86:89], v[176:179], v[208:211], v[86:89]
	v_mfma_f32_16x16x32_bf16 v[82:85], v[184:187], v[208:211], v[82:85]
	v_mfma_f32_16x16x32_bf16 v[70:73], v[176:179], v[216:219], v[70:73]
	v_mfma_f32_16x16x32_bf16 v[66:69], v[184:187], v[216:219], v[66:69]
	s_setprio 0
	s_barrier
	s_add_i32 s38, s64, s44
	v_lshl_add_u64 v[146:147], v[146:147], 0, s[10:11]
	s_mov_b32 m0, s38
	s_nop 0
	global_load_lds_dwordx4 v[146:147], off
	s_add_i32 m0, s38, 0x2000
	s_add_u32 s36, s36, 0x80080
	v_lshl_add_u64 v[146:147], v[220:221], 0, s[10:11]
	s_addc_u32 s37, s37, 0
	s_add_i32 s38, s65, s44
	global_load_lds_dwordx4 v[146:147], off
	v_lshl_add_u64 v[146:147], s[36:37], 0, v[132:133]
	s_mov_b32 m0, s38
	s_nop 0
	global_load_lds_dwordx4 v[146:147], off
	v_lshl_add_u64 v[146:147], s[36:37], 0, v[136:137]
	s_add_i32 m0, s38, 0x2000
	s_nop 0
	global_load_lds_dwordx4 v[146:147], off
	v_lshl_add_u64 v[146:147], v[222:223], 0, s[10:11]
	s_mov_b32 m0, s49
	s_nop 0
	global_load_lds_dwordx4 v[146:147], off
	v_lshl_add_u64 v[146:147], v[224:225], 0, s[10:11]
	s_mov_b32 m0, s50
	s_nop 0
	global_load_lds_dwordx4 v[146:147], off
	ds_read_b128 v[188:191], v155 offset:49152
	ds_read_b128 v[192:195], v155 offset:50176
	ds_read_b128 v[196:199], v155 offset:51200
	ds_read_b128 v[200:203], v155 offset:52224
	ds_read_b128 v[204:207], v155 offset:53248
	ds_read_b128 v[208:211], v155 offset:54272
	ds_read_b128 v[212:215], v155 offset:55296
	ds_read_b128 v[216:219], v155 offset:56320
	s_waitcnt vmcnt(8)
	s_waitcnt lgkmcnt(0)
	s_barrier
	s_setprio 1
	s_waitcnt lgkmcnt(0)
	v_mfma_f32_16x16x32_bf16 v[62:65], v[156:159], v[188:191], v[62:65]
	v_mfma_f32_16x16x32_bf16 v[58:61], v[164:167], v[188:191], v[58:61]
	v_mfma_f32_16x16x32_bf16 v[46:49], v[156:159], v[196:199], v[46:49]
	v_mfma_f32_16x16x32_bf16 v[42:45], v[164:167], v[196:199], v[42:45]
	v_mfma_f32_16x16x32_bf16 v[30:33], v[156:159], v[204:207], v[30:33]
	v_mfma_f32_16x16x32_bf16 v[26:29], v[164:167], v[204:207], v[26:29]
	v_mfma_f32_16x16x32_bf16 v[14:17], v[156:159], v[212:215], v[14:17]
	v_mfma_f32_16x16x32_bf16 v[10:13], v[164:167], v[212:215], v[10:13]
	v_mfma_f32_16x16x32_bf16 v[62:65], v[160:163], v[192:195], v[62:65]
	v_mfma_f32_16x16x32_bf16 v[58:61], v[168:171], v[192:195], v[58:61]
	v_mfma_f32_16x16x32_bf16 v[46:49], v[160:163], v[200:203], v[46:49]
	v_mfma_f32_16x16x32_bf16 v[42:45], v[168:171], v[200:203], v[42:45]
	v_mfma_f32_16x16x32_bf16 v[30:33], v[160:163], v[208:211], v[30:33]
	v_mfma_f32_16x16x32_bf16 v[26:29], v[168:171], v[208:211], v[26:29]
	v_mfma_f32_16x16x32_bf16 v[14:17], v[160:163], v[216:219], v[14:17]
	v_mfma_f32_16x16x32_bf16 v[10:13], v[168:171], v[216:219], v[10:13]
	s_setprio 0
	s_setprio 1
	v_mfma_f32_16x16x32_bf16 v[54:57], v[172:175], v[188:191], v[54:57]
	v_mfma_f32_16x16x32_bf16 v[50:53], v[180:183], v[188:191], v[50:53]
	v_mfma_f32_16x16x32_bf16 v[38:41], v[172:175], v[196:199], v[38:41]
	v_mfma_f32_16x16x32_bf16 v[34:37], v[180:183], v[196:199], v[34:37]
	v_mfma_f32_16x16x32_bf16 v[22:25], v[172:175], v[204:207], v[22:25]
	v_mfma_f32_16x16x32_bf16 v[18:21], v[180:183], v[204:207], v[18:21]
	v_mfma_f32_16x16x32_bf16 v[6:9], v[172:175], v[212:215], v[6:9]
	v_mfma_f32_16x16x32_bf16 v[2:5], v[180:183], v[212:215], v[2:5]
	v_mfma_f32_16x16x32_bf16 v[54:57], v[176:179], v[192:195], v[54:57]
	v_mfma_f32_16x16x32_bf16 v[50:53], v[184:187], v[192:195], v[50:53]
	v_mfma_f32_16x16x32_bf16 v[38:41], v[176:179], v[200:203], v[38:41]
	v_mfma_f32_16x16x32_bf16 v[34:37], v[184:187], v[200:203], v[34:37]
	v_mfma_f32_16x16x32_bf16 v[22:25], v[176:179], v[208:211], v[22:25]
	v_mfma_f32_16x16x32_bf16 v[18:21], v[184:187], v[208:211], v[18:21]
	v_mfma_f32_16x16x32_bf16 v[6:9], v[176:179], v[216:219], v[6:9]
	v_mfma_f32_16x16x32_bf16 v[2:5], v[184:187], v[216:219], v[2:5]
	s_setprio 0
	s_barrier
	s_add_i32 s63, s63, 2
	s_add_u32 s34, s34, 0x100
	s_addc_u32 s35, s35, 0
	s_add_u32 s61, s61, 0x100
	s_addc_u32 s62, s62, 0
	s_cmp_gt_u32 s63, 29
	s_cbranch_scc0 .LBB0_1082
	s_and_b64 vcc, exec, s[12:13]
	s_cbranch_vccz .LBB0_1085
	s_barrier

.LBB0_1190:
	s_add_u32 s36, s34, 0xffe00080
	s_addc_u32 s37, s35, -1
	s_cmpk_eq_i32 s63, 0x7c
	s_cselect_b32 s39, s25, s37
	s_cselect_b32 s38, s59, s36
	s_cselect_b32 s37, s23, s62
	s_cselect_b32 s36, s60, s61
	v_lshl_add_u64 v[146:147], s[34:35], 0, v[138:139]
	s_add_i32 m0, s31, 0xc000
	s_nop 0
	global_load_lds_dwordx4 v[146:147], off
	v_lshl_add_u64 v[146:147], s[34:35], 0, v[140:141]
	s_add_i32 m0, s31, 0xe000
	s_nop 0
	global_load_lds_dwordx4 v[146:147], off
	ds_read_b128 v[156:159], v151
	ds_read_b128 v[160:163], v151 offset:1024
	ds_read_b128 v[164:167], v151 offset:2048
	ds_read_b128 v[168:171], v151 offset:3072
	ds_read_b128 v[172:175], v154
	ds_read_b128 v[176:179], v154 offset:1024
	ds_read_b128 v[180:183], v154 offset:2048
	ds_read_b128 v[184:187], v154 offset:3072
	ds_read_b128 v[188:191], v155
	ds_read_b128 v[192:195], v155 offset:1024
	ds_read_b128 v[196:199], v155 offset:2048
	ds_read_b128 v[200:203], v155 offset:3072
	ds_read_b128 v[204:207], v155 offset:4096
	ds_read_b128 v[208:211], v155 offset:5120
	ds_read_b128 v[212:215], v155 offset:6144
	ds_read_b128 v[216:219], v155 offset:7168
	s_waitcnt vmcnt(8)
	s_waitcnt lgkmcnt(0)
	s_barrier
	s_setprio 1
	s_waitcnt lgkmcnt(0)
	v_mfma_f32_16x16x32_bf16 v[126:129], v[156:159], v[188:191], v[126:129]
	v_mfma_f32_16x16x32_bf16 v[122:125], v[164:167], v[188:191], v[122:125]
	v_mfma_f32_16x16x32_bf16 v[118:121], v[156:159], v[196:199], v[118:121]
	v_mfma_f32_16x16x32_bf16 v[110:113], v[164:167], v[196:199], v[110:113]
	v_mfma_f32_16x16x32_bf16 v[102:105], v[156:159], v[204:207], v[102:105]
	v_mfma_f32_16x16x32_bf16 v[94:97], v[164:167], v[204:207], v[94:97]
	v_mfma_f32_16x16x32_bf16 v[86:89], v[156:159], v[212:215], v[86:89]
	v_mfma_f32_16x16x32_bf16 v[78:81], v[164:167], v[212:215], v[78:81]
	v_mfma_f32_16x16x32_bf16 v[126:129], v[160:163], v[192:195], v[126:129]
	v_mfma_f32_16x16x32_bf16 v[122:125], v[168:171], v[192:195], v[122:125]
	v_mfma_f32_16x16x32_bf16 v[118:121], v[160:163], v[200:203], v[118:121]
	v_mfma_f32_16x16x32_bf16 v[110:113], v[168:171], v[200:203], v[110:113]
	v_mfma_f32_16x16x32_bf16 v[102:105], v[160:163], v[208:211], v[102:105]
	v_mfma_f32_16x16x32_bf16 v[94:97], v[168:171], v[208:211], v[94:97]
	v_mfma_f32_16x16x32_bf16 v[86:89], v[160:163], v[216:219], v[86:89]
	v_mfma_f32_16x16x32_bf16 v[78:81], v[168:171], v[216:219], v[78:81]
	s_setprio 0
	s_setprio 1
	v_mfma_f32_16x16x32_bf16 v[114:117], v[172:175], v[188:191], v[114:117]
	v_mfma_f32_16x16x32_bf16 v[106:109], v[180:183], v[188:191], v[106:109]
	v_mfma_f32_16x16x32_bf16 v[98:101], v[172:175], v[196:199], v[98:101]
	v_mfma_f32_16x16x32_bf16 v[90:93], v[180:183], v[196:199], v[90:93]
	v_mfma_f32_16x16x32_bf16 v[82:85], v[172:175], v[204:207], v[82:85]
	v_mfma_f32_16x16x32_bf16 v[74:77], v[180:183], v[204:207], v[74:77]
	v_mfma_f32_16x16x32_bf16 v[70:73], v[172:175], v[212:215], v[70:73]
	v_mfma_f32_16x16x32_bf16 v[66:69], v[180:183], v[212:215], v[66:69]
	v_mfma_f32_16x16x32_bf16 v[114:117], v[176:179], v[192:195], v[114:117]
	v_mfma_f32_16x16x32_bf16 v[106:109], v[184:187], v[192:195], v[106:109]
	v_mfma_f32_16x16x32_bf16 v[98:101], v[176:179], v[200:203], v[98:101]
	v_mfma_f32_16x16x32_bf16 v[90:93], v[184:187], v[200:203], v[90:93]
	v_mfma_f32_16x16x32_bf16 v[82:85], v[176:179], v[208:211], v[82:85]
	v_mfma_f32_16x16x32_bf16 v[74:77], v[184:187], v[208:211], v[74:77]
	v_mfma_f32_16x16x32_bf16 v[70:73], v[176:179], v[216:219], v[70:73]
	v_mfma_f32_16x16x32_bf16 v[66:69], v[184:187], v[216:219], v[66:69]
	s_setprio 0
	s_barrier
	s_add_i32 s64, s52, s44
	v_lshl_add_u64 v[146:147], s[36:37], 0, v[132:133]
	s_mov_b32 m0, s64
	s_nop 0
	global_load_lds_dwordx4 v[146:147], off
	s_add_i32 m0, s64, 0x2000
	s_add_u32 s64, s36, 0x200000
	v_lshl_add_u64 v[220:221], s[36:37], 0, v[136:137]
	s_addc_u32 s65, s37, 0
	s_add_i32 s66, s53, s44
	global_load_lds_dwordx4 v[220:221], off
	v_lshl_add_u64 v[222:223], s[64:65], 0, v[132:133]
	s_mov_b32 m0, s66
	v_lshl_add_u64 v[224:225], s[38:39], 0, v[134:135]
	global_load_lds_dwordx4 v[222:223], off
	v_lshl_add_u64 v[222:223], s[64:65], 0, v[136:137]
	s_add_i32 m0, s66, 0x2000
	s_nop 0
	global_load_lds_dwordx4 v[222:223], off
	v_lshl_add_u64 v[222:223], s[38:39], 0, v[130:131]
	s_mov_b32 m0, s31
	s_nop 0
	global_load_lds_dwordx4 v[222:223], off
	s_mov_b32 m0, s45
	s_nop 0
	global_load_lds_dwordx4 v[224:225], off
	ds_read_b128 v[188:191], v155 offset:16384
	ds_read_b128 v[192:195], v155 offset:17408
	ds_read_b128 v[196:199], v155 offset:18432
	ds_read_b128 v[200:203], v155 offset:19456
	ds_read_b128 v[204:207], v155 offset:20480
	ds_read_b128 v[208:211], v155 offset:21504
	ds_read_b128 v[212:215], v155 offset:22528
	ds_read_b128 v[216:219], v155 offset:23552
	s_waitcnt vmcnt(8)
	s_waitcnt lgkmcnt(0)
	s_barrier
	s_setprio 1
	s_waitcnt lgkmcnt(0)
	v_mfma_f32_16x16x32_bf16 v[62:65], v[156:159], v[188:191], v[62:65]
	v_mfma_f32_16x16x32_bf16 v[58:61], v[164:167], v[188:191], v[58:61]
	v_mfma_f32_16x16x32_bf16 v[54:57], v[156:159], v[196:199], v[54:57]
	v_mfma_f32_16x16x32_bf16 v[46:49], v[164:167], v[196:199], v[46:49]
	v_mfma_f32_16x16x32_bf16 v[38:41], v[156:159], v[204:207], v[38:41]
	v_mfma_f32_16x16x32_bf16 v[30:33], v[164:167], v[204:207], v[30:33]
	v_mfma_f32_16x16x32_bf16 v[22:25], v[156:159], v[212:215], v[22:25]
	v_mfma_f32_16x16x32_bf16 v[14:17], v[164:167], v[212:215], v[14:17]
	v_mfma_f32_16x16x32_bf16 v[62:65], v[160:163], v[192:195], v[62:65]
	v_mfma_f32_16x16x32_bf16 v[58:61], v[168:171], v[192:195], v[58:61]
	v_mfma_f32_16x16x32_bf16 v[54:57], v[160:163], v[200:203], v[54:57]
	v_mfma_f32_16x16x32_bf16 v[46:49], v[168:171], v[200:203], v[46:49]
	v_mfma_f32_16x16x32_bf16 v[38:41], v[160:163], v[208:211], v[38:41]
	v_mfma_f32_16x16x32_bf16 v[30:33], v[168:171], v[208:211], v[30:33]
	v_mfma_f32_16x16x32_bf16 v[22:25], v[160:163], v[216:219], v[22:25]
	v_mfma_f32_16x16x32_bf16 v[14:17], v[168:171], v[216:219], v[14:17]
	s_setprio 0
	s_setprio 1
	v_mfma_f32_16x16x32_bf16 v[50:53], v[172:175], v[188:191], v[50:53]
	v_mfma_f32_16x16x32_bf16 v[42:45], v[180:183], v[188:191], v[42:45]
	v_mfma_f32_16x16x32_bf16 v[34:37], v[172:175], v[196:199], v[34:37]
	v_mfma_f32_16x16x32_bf16 v[26:29], v[180:183], v[196:199], v[26:29]
	v_mfma_f32_16x16x32_bf16 v[18:21], v[172:175], v[204:207], v[18:21]
	v_mfma_f32_16x16x32_bf16 v[10:13], v[180:183], v[204:207], v[10:13]
	v_mfma_f32_16x16x32_bf16 v[6:9], v[172:175], v[212:215], v[6:9]
	v_mfma_f32_16x16x32_bf16 v[2:5], v[180:183], v[212:215], v[2:5]
	v_mfma_f32_16x16x32_bf16 v[50:53], v[176:179], v[192:195], v[50:53]
	v_mfma_f32_16x16x32_bf16 v[42:45], v[184:187], v[192:195], v[42:45]
	v_mfma_f32_16x16x32_bf16 v[34:37], v[176:179], v[200:203], v[34:37]
	v_mfma_f32_16x16x32_bf16 v[26:29], v[184:187], v[200:203], v[26:29]
	v_mfma_f32_16x16x32_bf16 v[18:21], v[176:179], v[208:211], v[18:21]
	v_mfma_f32_16x16x32_bf16 v[10:13], v[184:187], v[208:211], v[10:13]
	v_mfma_f32_16x16x32_bf16 v[6:9], v[176:179], v[216:219], v[6:9]
	v_mfma_f32_16x16x32_bf16 v[2:5], v[184:187], v[216:219], v[2:5]
	s_setprio 0
	s_barrier
	s_add_i32 s64, 0, 0x18000
	s_add_i32 s65, 0, 0x1c000
	v_add_u32_e32 v168, s64, v149
	v_add_u32_e32 v184, s65, v149
	ds_read_b128 v[156:159], v168
	ds_read_b128 v[160:163], v168 offset:1024
	ds_read_b128 v[164:167], v168 offset:2048
	ds_read_b128 v[168:171], v168 offset:3072
	ds_read_b128 v[172:175], v184
	ds_read_b128 v[176:179], v184 offset:1024
	ds_read_b128 v[180:183], v184 offset:2048
	ds_read_b128 v[184:187], v184 offset:3072
	s_add_u32 s38, s38, 0x200000
	s_addc_u32 s39, s39, 0
	s_mov_b32 m0, s46
	v_lshl_add_u64 v[226:227], s[38:39], 0, v[130:131]
	ds_read_b128 v[188:191], v155 offset:32768
	ds_read_b128 v[192:195], v155 offset:33792
	ds_read_b128 v[196:199], v155 offset:34816
	ds_read_b128 v[200:203], v155 offset:35840
	ds_read_b128 v[204:207], v155 offset:36864
	ds_read_b128 v[208:211], v155 offset:37888
	ds_read_b128 v[212:215], v155 offset:38912
	ds_read_b128 v[216:219], v155 offset:39936
	global_load_lds_dwordx4 v[226:227], off
	v_lshl_add_u64 v[226:227], s[38:39], 0, v[134:135]
	s_mov_b32 m0, s47
	s_nop 0
	global_load_lds_dwordx4 v[226:227], off
	s_waitcnt vmcnt(8)
	s_waitcnt lgkmcnt(0)
	s_barrier
	s_setprio 1
	s_waitcnt lgkmcnt(0)
	v_mfma_f32_16x16x32_bf16 v[126:129], v[156:159], v[188:191], v[126:129]
	v_mfma_f32_16x16x32_bf16 v[122:125], v[164:167], v[188:191], v[122:125]
	v_mfma_f32_16x16x32_bf16 v[118:121], v[156:159], v[196:199], v[118:121]
	v_mfma_f32_16x16x32_bf16 v[110:113], v[164:167], v[196:199], v[110:113]
	v_mfma_f32_16x16x32_bf16 v[102:105], v[156:159], v[204:207], v[102:105]
	v_mfma_f32_16x16x32_bf16 v[94:97], v[164:167], v[204:207], v[94:97]
	v_mfma_f32_16x16x32_bf16 v[86:89], v[156:159], v[212:215], v[86:89]
	v_mfma_f32_16x16x32_bf16 v[78:81], v[164:167], v[212:215], v[78:81]
	v_mfma_f32_16x16x32_bf16 v[126:129], v[160:163], v[192:195], v[126:129]
	v_mfma_f32_16x16x32_bf16 v[122:125], v[168:171], v[192:195], v[122:125]
	v_mfma_f32_16x16x32_bf16 v[118:121], v[160:163], v[200:203], v[118:121]
	v_mfma_f32_16x16x32_bf16 v[110:113], v[168:171], v[200:203], v[110:113]
	v_mfma_f32_16x16x32_bf16 v[102:105], v[160:163], v[208:211], v[102:105]
	v_mfma_f32_16x16x32_bf16 v[94:97], v[168:171], v[208:211], v[94:97]
	v_mfma_f32_16x16x32_bf16 v[86:89], v[160:163], v[216:219], v[86:89]
	v_mfma_f32_16x16x32_bf16 v[78:81], v[168:171], v[216:219], v[78:81]
	s_setprio 0
	s_setprio 1
	v_mfma_f32_16x16x32_bf16 v[114:117], v[172:175], v[188:191], v[114:117]
	v_mfma_f32_16x16x32_bf16 v[106:109], v[180:183], v[188:191], v[106:109]
	v_mfma_f32_16x16x32_bf16 v[98:101], v[172:175], v[196:199], v[98:101]
	v_mfma_f32_16x16x32_bf16 v[90:93], v[180:183], v[196:199], v[90:93]
	v_mfma_f32_16x16x32_bf16 v[82:85], v[172:175], v[204:207], v[82:85]
	v_mfma_f32_16x16x32_bf16 v[74:77], v[180:183], v[204:207], v[74:77]
	v_mfma_f32_16x16x32_bf16 v[70:73], v[172:175], v[212:215], v[70:73]
	v_mfma_f32_16x16x32_bf16 v[66:69], v[180:183], v[212:215], v[66:69]
	v_mfma_f32_16x16x32_bf16 v[114:117], v[176:179], v[192:195], v[114:117]
	v_mfma_f32_16x16x32_bf16 v[106:109], v[184:187], v[192:195], v[106:109]
	v_mfma_f32_16x16x32_bf16 v[98:101], v[176:179], v[200:203], v[98:101]
	v_mfma_f32_16x16x32_bf16 v[90:93], v[184:187], v[200:203], v[90:93]
	v_mfma_f32_16x16x32_bf16 v[82:85], v[176:179], v[208:211], v[82:85]
	v_mfma_f32_16x16x32_bf16 v[74:77], v[184:187], v[208:211], v[74:77]
	v_mfma_f32_16x16x32_bf16 v[70:73], v[176:179], v[216:219], v[70:73]
	v_mfma_f32_16x16x32_bf16 v[66:69], v[184:187], v[216:219], v[66:69]
	s_setprio 0
	s_barrier
	s_add_i32 s38, s64, s44
	v_lshl_add_u64 v[146:147], v[146:147], 0, s[10:11]
	s_mov_b32 m0, s38
	s_nop 0
	global_load_lds_dwordx4 v[146:147], off
	s_add_i32 m0, s38, 0x2000
	s_add_u32 s36, s36, 0x200080
	v_lshl_add_u64 v[146:147], v[220:221], 0, s[10:11]
	s_addc_u32 s37, s37, 0
	s_add_i32 s38, s65, s44
	global_load_lds_dwordx4 v[146:147], off
	v_lshl_add_u64 v[146:147], s[36:37], 0, v[132:133]
	s_mov_b32 m0, s38
	s_nop 0
	global_load_lds_dwordx4 v[146:147], off
	v_lshl_add_u64 v[146:147], s[36:37], 0, v[136:137]
	s_add_i32 m0, s38, 0x2000
	s_nop 0
	global_load_lds_dwordx4 v[146:147], off
	v_lshl_add_u64 v[146:147], v[222:223], 0, s[10:11]
	s_mov_b32 m0, s49
	s_nop 0
	global_load_lds_dwordx4 v[146:147], off
	v_lshl_add_u64 v[146:147], v[224:225], 0, s[10:11]
	s_mov_b32 m0, s50
	s_nop 0
	global_load_lds_dwordx4 v[146:147], off
	ds_read_b128 v[188:191], v155 offset:49152
	ds_read_b128 v[192:195], v155 offset:50176
	ds_read_b128 v[196:199], v155 offset:51200
	ds_read_b128 v[200:203], v155 offset:52224
	ds_read_b128 v[204:207], v155 offset:53248
	ds_read_b128 v[208:211], v155 offset:54272
	ds_read_b128 v[212:215], v155 offset:55296
	ds_read_b128 v[216:219], v155 offset:56320
	s_waitcnt vmcnt(8)
	s_waitcnt lgkmcnt(0)
	s_barrier
	s_setprio 1
	s_waitcnt lgkmcnt(0)
	v_mfma_f32_16x16x32_bf16 v[62:65], v[156:159], v[188:191], v[62:65]
	v_mfma_f32_16x16x32_bf16 v[58:61], v[164:167], v[188:191], v[58:61]
	v_mfma_f32_16x16x32_bf16 v[54:57], v[156:159], v[196:199], v[54:57]
	v_mfma_f32_16x16x32_bf16 v[46:49], v[164:167], v[196:199], v[46:49]
	v_mfma_f32_16x16x32_bf16 v[38:41], v[156:159], v[204:207], v[38:41]
	v_mfma_f32_16x16x32_bf16 v[30:33], v[164:167], v[204:207], v[30:33]
	v_mfma_f32_16x16x32_bf16 v[22:25], v[156:159], v[212:215], v[22:25]
	v_mfma_f32_16x16x32_bf16 v[14:17], v[164:167], v[212:215], v[14:17]
	v_mfma_f32_16x16x32_bf16 v[62:65], v[160:163], v[192:195], v[62:65]
	v_mfma_f32_16x16x32_bf16 v[58:61], v[168:171], v[192:195], v[58:61]
	v_mfma_f32_16x16x32_bf16 v[54:57], v[160:163], v[200:203], v[54:57]
	v_mfma_f32_16x16x32_bf16 v[46:49], v[168:171], v[200:203], v[46:49]
	v_mfma_f32_16x16x32_bf16 v[38:41], v[160:163], v[208:211], v[38:41]
	v_mfma_f32_16x16x32_bf16 v[30:33], v[168:171], v[208:211], v[30:33]
	v_mfma_f32_16x16x32_bf16 v[22:25], v[160:163], v[216:219], v[22:25]
	v_mfma_f32_16x16x32_bf16 v[14:17], v[168:171], v[216:219], v[14:17]
	s_setprio 0
	s_setprio 1
	v_mfma_f32_16x16x32_bf16 v[50:53], v[172:175], v[188:191], v[50:53]
	v_mfma_f32_16x16x32_bf16 v[42:45], v[180:183], v[188:191], v[42:45]
	v_mfma_f32_16x16x32_bf16 v[34:37], v[172:175], v[196:199], v[34:37]
	v_mfma_f32_16x16x32_bf16 v[26:29], v[180:183], v[196:199], v[26:29]
	v_mfma_f32_16x16x32_bf16 v[18:21], v[172:175], v[204:207], v[18:21]
	v_mfma_f32_16x16x32_bf16 v[10:13], v[180:183], v[204:207], v[10:13]
	v_mfma_f32_16x16x32_bf16 v[6:9], v[172:175], v[212:215], v[6:9]
	v_mfma_f32_16x16x32_bf16 v[2:5], v[180:183], v[212:215], v[2:5]
	v_mfma_f32_16x16x32_bf16 v[50:53], v[176:179], v[192:195], v[50:53]
	v_mfma_f32_16x16x32_bf16 v[42:45], v[184:187], v[192:195], v[42:45]
	v_mfma_f32_16x16x32_bf16 v[34:37], v[176:179], v[200:203], v[34:37]
	v_mfma_f32_16x16x32_bf16 v[26:29], v[184:187], v[200:203], v[26:29]
	v_mfma_f32_16x16x32_bf16 v[18:21], v[176:179], v[208:211], v[18:21]
	v_mfma_f32_16x16x32_bf16 v[10:13], v[184:187], v[208:211], v[10:13]
	v_mfma_f32_16x16x32_bf16 v[6:9], v[176:179], v[216:219], v[6:9]
	v_mfma_f32_16x16x32_bf16 v[2:5], v[184:187], v[216:219], v[2:5]
	s_setprio 0
	s_barrier
	s_add_i32 s63, s63, 2
	s_add_u32 s34, s34, 0x100
	s_addc_u32 s35, s35, 0
	s_add_u32 s61, s61, 0x100
	s_addc_u32 s62, s62, 0
	s_cmpk_gt_u32 s63, 0x7d
	s_cbranch_scc0 .LBB0_1190
	s_and_b64 vcc, exec, s[12:13]
	s_cbranch_vccz .LBB0_1193
	s_barrier
